# P2/P5/P7 epilogues: bf16 residual loads widened to dwordx4 (+v_permlane16_swap), counted waits re-derived
# speedup vs baseline: 1.0384x; 1.0085x over previous
.LBB0_263:
	v_mbcnt_lo_u32_b32 v242, -1, 0
	v_mbcnt_hi_u32_b32 v242, -1, v242
	v_bfe_u32 v242, v242, 4, 1
	v_mul_u32_u24_e32 v242, 24, v242
	v_mov_b32_e32 v243, 0
	v_lshl_or_b32 v140, s77, 8, v180
	v_lshl_add_u32 v184, s76, 8, v176
	v_ashrrev_i32_e32 v141, 31, v140
	v_lshlrev_b64 v[186:187], 1, v[140:141]
	v_ashrrev_i32_e32 v185, 31, v184
	v_lshl_add_u64 v[142:143], s[34:35], 0, v[186:187]
	v_lshlrev_b64 v[144:145], 12, v[184:185]
	v_lshl_add_u64 v[146:147], v[142:143], 0, v[144:145]
	v_lshl_add_u64 v[252:253], v[146:147], 0, v[242:243]
	global_load_dwordx4 v[208:211], v[252:253], off
	v_lshl_add_u64 v[252:253], v[146:147], 0, v[242:243]
	global_load_dwordx4 v[212:215], v[252:253], off offset:256
	v_or_b32_e32 v146, 16, v184
	v_or_b32_e32 v148, 32, v184
	v_or_b32_e32 v150, 48, v184
	v_ashrrev_i32_e32 v147, 31, v146
	v_ashrrev_i32_e32 v149, 31, v148
	v_ashrrev_i32_e32 v151, 31, v150
	v_lshlrev_b64 v[166:167], 12, v[146:147]
	v_lshlrev_b64 v[156:157], 12, v[148:149]
	v_lshlrev_b64 v[146:147], 12, v[150:151]
	v_lshl_add_u64 v[148:149], v[142:143], 0, v[166:167]
	v_lshl_add_u64 v[150:151], v[142:143], 0, v[156:157]
	v_lshl_add_u64 v[196:197], v[142:143], 0, v[146:147]
	v_lshl_add_u64 v[252:253], v[148:149], 0, v[242:243]
	global_load_dwordx4 v[216:219], v[252:253], off
	v_lshl_add_u64 v[252:253], v[148:149], 0, v[242:243]
	global_load_dwordx4 v[220:223], v[252:253], off offset:256
	v_lshl_add_u64 v[252:253], v[150:151], 0, v[242:243]
	global_load_dwordx4 v[224:227], v[252:253], off
	v_lshl_add_u64 v[252:253], v[150:151], 0, v[242:243]
	global_load_dwordx4 v[228:231], v[252:253], off offset:256
	v_lshl_add_u64 v[252:253], v[196:197], 0, v[242:243]
	global_load_dwordx4 v[244:247], v[252:253], off
	s_nop 0
	v_lshl_add_u64 v[252:253], v[196:197], 0, v[242:243]
	global_load_dwordx4 v[248:251], v[252:253], off offset:256
	v_lshl_add_u64 v[196:197], s[34:35], 0, v[144:145]
	v_lshl_add_u64 v[186:187], v[196:197], 0, v[186:187]
	s_waitcnt vmcnt(0)
	v_permlane16_swap_b32 v208, v210
	v_permlane16_swap_b32 v209, v211
	v_lshlrev_b32_e32 v196, 16, v208
	v_and_b32_e32 v197, 0xffff0000, v208
	v_lshlrev_b32_e32 v188, 16, v209
	v_and_b32_e32 v189, 0xffff0000, v209
	v_lshlrev_b32_e32 v198, 16, v210
	v_and_b32_e32 v199, 0xffff0000, v210
	v_lshlrev_b32_e32 v190, 16, v211
	v_and_b32_e32 v191, 0xffff0000, v211
	v_permlane16_swap_b32 v212, v214
	v_permlane16_swap_b32 v213, v215
	v_lshlrev_b32_e32 v200, 16, v212
	v_and_b32_e32 v201, 0xffff0000, v212
	v_lshlrev_b32_e32 v192, 16, v213
	v_and_b32_e32 v193, 0xffff0000, v213
	v_lshlrev_b32_e32 v202, 16, v214
	v_and_b32_e32 v203, 0xffff0000, v214
	v_lshlrev_b32_e32 v194, 16, v215
	v_and_b32_e32 v195, 0xffff0000, v215
	v_pk_fma_f32 v[126:127], v[126:127], 0.5, v[188:189] op_sel_hi:[1,0,1]
	v_pk_fma_f32 v[124:125], v[124:125], 0.5, v[196:197] op_sel_hi:[1,0,1]
	v_pk_fma_f32 v[122:123], v[122:123], 0.5, v[190:191] op_sel_hi:[1,0,1]
	v_pk_fma_f32 v[120:121], v[120:121], 0.5, v[198:199] op_sel_hi:[1,0,1]
	v_pk_fma_f32 v[118:119], v[118:119], 0.5, v[192:193] op_sel_hi:[1,0,1]
	v_pk_fma_f32 v[116:117], v[116:117], 0.5, v[200:201] op_sel_hi:[1,0,1]
	v_pk_fma_f32 v[188:189], v[114:115], 0.5, v[194:195] op_sel_hi:[1,0,1]
	v_mul_f32_e32 v190, v125, v125
	v_mul_f32_e32 v191, v127, v127
	v_cvt_pk_bf16_f32 v232, v124, v125
	v_cvt_pk_bf16_f32 v233, v126, v127
	v_mul_f32_e32 v125, v121, v121
	v_mul_f32_e32 v127, v123, v123
	v_pk_fma_f32 v[112:113], v[112:113], 0.5, v[202:203] op_sel_hi:[1,0,1]
	v_mul_f32_e32 v192, v117, v117
	v_mul_f32_e32 v193, v119, v119
	v_fmac_f32_e32 v190, v124, v124
	v_fmac_f32_e32 v191, v126, v126
	v_fmac_f32_e32 v125, v120, v120
	v_fmac_f32_e32 v127, v122, v122
	v_mul_f32_e32 v194, v113, v113
	v_mul_f32_e32 v195, v189, v189
	v_cvt_pk_bf16_f32 v234, v120, v121
	v_fmac_f32_e32 v192, v116, v116
	v_fmac_f32_e32 v193, v118, v118
	v_add_f32_e32 v120, v190, v191
	v_add_f32_e32 v121, v125, v127
	v_cvt_pk_bf16_f32 v235, v122, v123
	v_fmac_f32_e32 v194, v112, v112
	v_fmac_f32_e32 v195, v188, v188
	v_add_f32_e32 v122, v192, v193
	v_add_f32_e32 v120, v120, v121
	v_add_f32_e32 v120, v120, v122
	v_add_f32_e32 v121, v194, v195
	v_add_f32_e32 v120, v120, v121
	ds_bpermute_b32 v121, v178, v120
	s_nop 1
	v_permlane16_swap_b32 v232, v234
	v_permlane16_swap_b32 v233, v235
	v_lshl_add_u64 v[240:241], v[186:187], 0, v[242:243]
	global_store_dwordx4 v[240:241], v[232:235], off
	v_cvt_pk_bf16_f32 v236, v116, v117
	v_cvt_pk_bf16_f32 v237, v118, v119
	s_waitcnt lgkmcnt(0)
	v_add_f32_e32 v114, v120, v121
	ds_bpermute_b32 v115, v179, v114
	v_cvt_pk_bf16_f32 v238, v112, v113
	v_cvt_pk_bf16_f32 v239, v188, v189
	s_nop 1
	v_permlane16_swap_b32 v236, v238
	v_permlane16_swap_b32 v237, v239
	v_lshl_add_u64 v[240:241], v[186:187], 0, v[242:243]
	global_store_dwordx4 v[240:241], v[236:239], off offset:256
	v_lshl_add_u64 v[112:113], v[184:185], 2, s[26:27]
	s_and_saveexec_b64 s[50:51], s[6:7]
	s_cbranch_execz .LBB0_265
	s_waitcnt lgkmcnt(0)
	v_add_f32_e32 v114, v114, v115
	global_atomic_add_f32 v[112:113], v114, off
.LBB0_265:
	s_or_b64 exec, exec, s[50:51]
	v_permlane16_swap_b32 v216, v218
	v_permlane16_swap_b32 v217, v219
	v_lshlrev_b32_e32 v114, 16, v216
	s_waitcnt lgkmcnt(0)
	v_and_b32_e32 v115, 0xffff0000, v216
	v_lshlrev_b32_e32 v116, 16, v217
	v_and_b32_e32 v117, 0xffff0000, v217
	v_pk_fma_f32 v[110:111], v[110:111], 0.5, v[116:117] op_sel_hi:[1,0,1]
	v_pk_fma_f32 v[108:109], v[108:109], 0.5, v[114:115] op_sel_hi:[1,0,1]
	v_mul_f32_e32 v115, v111, v111
	v_mul_f32_e32 v114, v109, v109
	v_lshlrev_b32_e32 v118, 16, v218
	v_and_b32_e32 v119, 0xffff0000, v218
	v_lshlrev_b32_e32 v120, 16, v219
	v_and_b32_e32 v121, 0xffff0000, v219
	v_fmac_f32_e32 v114, v108, v108
	v_fmac_f32_e32 v115, v110, v110
	v_cvt_pk_bf16_f32 v232, v108, v109
	v_cvt_pk_bf16_f32 v233, v110, v111
	v_lshl_add_u64 v[110:111], s[34:35], 0, v[166:167]
	v_lshl_add_u64 v[110:111], v[140:141], 1, v[110:111]
	v_pk_fma_f32 v[106:107], v[106:107], 0.5, v[120:121] op_sel_hi:[1,0,1]
	v_pk_fma_f32 v[104:105], v[104:105], 0.5, v[118:119] op_sel_hi:[1,0,1]
	v_permlane16_swap_b32 v220, v222
	v_permlane16_swap_b32 v221, v223
	v_lshlrev_b32_e32 v122, 16, v220
	v_and_b32_e32 v123, 0xffff0000, v220
	v_lshlrev_b32_e32 v124, 16, v221
	v_and_b32_e32 v125, 0xffff0000, v221
	v_mul_f32_e32 v108, v105, v105
	v_mul_f32_e32 v109, v107, v107
	v_fmac_f32_e32 v108, v104, v104
	v_fmac_f32_e32 v109, v106, v106
	v_pk_fma_f32 v[102:103], v[102:103], 0.5, v[124:125] op_sel_hi:[1,0,1]
	v_pk_fma_f32 v[100:101], v[100:101], 0.5, v[122:123] op_sel_hi:[1,0,1]
	v_add_f32_e32 v108, v108, v109
	v_cvt_pk_bf16_f32 v234, v104, v105
	v_mul_f32_e32 v105, v101, v101
	v_mul_f32_e32 v109, v103, v103
	v_add_f32_e32 v114, v114, v115
	v_fmac_f32_e32 v105, v100, v100
	v_fmac_f32_e32 v109, v102, v102
	v_lshlrev_b32_e32 v126, 16, v222
	v_and_b32_e32 v127, 0xffff0000, v222
	v_lshlrev_b32_e32 v168, 16, v223
	v_and_b32_e32 v169, 0xffff0000, v223
	v_add_f32_e32 v108, v114, v108
	v_add_f32_e32 v105, v105, v109
	v_add_f32_e32 v105, v108, v105
	v_pk_fma_f32 v[98:99], v[98:99], 0.5, v[168:169] op_sel_hi:[1,0,1]
	v_pk_fma_f32 v[108:109], v[96:97], 0.5, v[126:127] op_sel_hi:[1,0,1]
	v_mul_f32_e32 v97, v99, v99
	v_mul_f32_e32 v96, v109, v109
	v_fmac_f32_e32 v96, v108, v108
	v_fmac_f32_e32 v97, v98, v98
	v_add_f32_e32 v96, v96, v97
	v_add_f32_e32 v96, v105, v96
	ds_bpermute_b32 v97, v178, v96
	v_cvt_pk_bf16_f32 v235, v106, v107
	s_nop 1
	v_permlane16_swap_b32 v232, v234
	v_permlane16_swap_b32 v233, v235
	v_lshl_add_u64 v[240:241], v[110:111], 0, v[242:243]
	global_store_dwordx4 v[240:241], v[232:235], off
	v_cvt_pk_bf16_f32 v236, v100, v101
	v_cvt_pk_bf16_f32 v237, v102, v103
	s_waitcnt lgkmcnt(0)
	v_add_f32_e32 v96, v96, v97
	ds_bpermute_b32 v97, v179, v96
	v_cvt_pk_bf16_f32 v238, v108, v109
	v_cvt_pk_bf16_f32 v239, v98, v99
	s_nop 1
	v_permlane16_swap_b32 v236, v238
	v_permlane16_swap_b32 v237, v239
	v_lshl_add_u64 v[240:241], v[110:111], 0, v[242:243]
	global_store_dwordx4 v[240:241], v[236:239], off offset:256
	s_and_saveexec_b64 s[50:51], s[6:7]
	s_cbranch_execz .LBB0_267
	s_waitcnt lgkmcnt(0)
	v_add_f32_e32 v96, v96, v97
	global_atomic_add_f32 v[112:113], v96, off offset:64
.LBB0_267:
	s_or_b64 exec, exec, s[50:51]
	v_permlane16_swap_b32 v224, v226
	v_permlane16_swap_b32 v225, v227
	v_lshlrev_b32_e32 v96, 16, v224
	s_waitcnt lgkmcnt(0)
	v_and_b32_e32 v97, 0xffff0000, v224
	v_lshlrev_b32_e32 v98, 16, v225
	v_and_b32_e32 v99, 0xffff0000, v225
	v_pk_fma_f32 v[94:95], v[94:95], 0.5, v[98:99] op_sel_hi:[1,0,1]
	v_pk_fma_f32 v[92:93], v[92:93], 0.5, v[96:97] op_sel_hi:[1,0,1]
	v_mul_f32_e32 v97, v95, v95
	v_mul_f32_e32 v96, v93, v93
	v_lshlrev_b32_e32 v100, 16, v226
	v_and_b32_e32 v101, 0xffff0000, v226
	v_lshlrev_b32_e32 v102, 16, v227
	v_and_b32_e32 v103, 0xffff0000, v227
	v_fmac_f32_e32 v96, v92, v92
	v_fmac_f32_e32 v97, v94, v94
	v_cvt_pk_bf16_f32 v232, v92, v93
	v_cvt_pk_bf16_f32 v233, v94, v95
	v_lshl_add_u64 v[94:95], s[34:35], 0, v[156:157]
	v_lshl_add_u64 v[94:95], v[140:141], 1, v[94:95]
	v_pk_fma_f32 v[90:91], v[90:91], 0.5, v[102:103] op_sel_hi:[1,0,1]
	v_pk_fma_f32 v[88:89], v[88:89], 0.5, v[100:101] op_sel_hi:[1,0,1]
	v_permlane16_swap_b32 v228, v230
	v_permlane16_swap_b32 v229, v231
	v_lshlrev_b32_e32 v104, 16, v228
	v_and_b32_e32 v105, 0xffff0000, v228
	v_lshlrev_b32_e32 v106, 16, v229
	v_and_b32_e32 v107, 0xffff0000, v229
	v_mul_f32_e32 v92, v89, v89
	v_mul_f32_e32 v93, v91, v91
	v_fmac_f32_e32 v92, v88, v88
	v_fmac_f32_e32 v93, v90, v90
	v_pk_fma_f32 v[86:87], v[86:87], 0.5, v[106:107] op_sel_hi:[1,0,1]
	v_pk_fma_f32 v[84:85], v[84:85], 0.5, v[104:105] op_sel_hi:[1,0,1]
	v_add_f32_e32 v92, v92, v93
	v_cvt_pk_bf16_f32 v234, v88, v89
	v_mul_f32_e32 v89, v85, v85
	v_mul_f32_e32 v93, v87, v87
	v_add_f32_e32 v96, v96, v97
	v_fmac_f32_e32 v89, v84, v84
	v_fmac_f32_e32 v93, v86, v86
	v_lshlrev_b32_e32 v108, 16, v230
	v_and_b32_e32 v109, 0xffff0000, v230
	v_lshlrev_b32_e32 v110, 16, v231
	v_and_b32_e32 v111, 0xffff0000, v231
	v_add_f32_e32 v92, v96, v92
	v_add_f32_e32 v89, v89, v93
	v_add_f32_e32 v89, v92, v89
	v_pk_fma_f32 v[82:83], v[82:83], 0.5, v[110:111] op_sel_hi:[1,0,1]
	v_pk_fma_f32 v[92:93], v[80:81], 0.5, v[108:109] op_sel_hi:[1,0,1]
	v_mul_f32_e32 v81, v83, v83
	v_mul_f32_e32 v80, v93, v93
	v_fmac_f32_e32 v80, v92, v92
	v_fmac_f32_e32 v81, v82, v82
	v_add_f32_e32 v80, v80, v81
	v_add_f32_e32 v80, v89, v80
	ds_bpermute_b32 v81, v178, v80
	v_cvt_pk_bf16_f32 v235, v90, v91
	s_nop 1
	v_permlane16_swap_b32 v232, v234
	v_permlane16_swap_b32 v233, v235
	v_lshl_add_u64 v[240:241], v[94:95], 0, v[242:243]
	global_store_dwordx4 v[240:241], v[232:235], off
	v_cvt_pk_bf16_f32 v236, v84, v85
	v_cvt_pk_bf16_f32 v237, v86, v87
	s_waitcnt lgkmcnt(0)
	v_add_f32_e32 v80, v80, v81
	ds_bpermute_b32 v81, v179, v80
	v_cvt_pk_bf16_f32 v238, v92, v93
	v_cvt_pk_bf16_f32 v239, v82, v83
	s_nop 1
	v_permlane16_swap_b32 v236, v238
	v_permlane16_swap_b32 v237, v239
	v_lshl_add_u64 v[240:241], v[94:95], 0, v[242:243]
	global_store_dwordx4 v[240:241], v[236:239], off offset:256
	s_and_saveexec_b64 s[50:51], s[6:7]
	s_cbranch_execz .LBB0_269
	s_waitcnt lgkmcnt(0)
	v_add_f32_e32 v80, v80, v81
	global_atomic_add_f32 v[112:113], v80, off offset:128
.LBB0_269:
	s_or_b64 exec, exec, s[50:51]
	v_permlane16_swap_b32 v244, v246
	v_permlane16_swap_b32 v245, v247
	v_lshlrev_b32_e32 v80, 16, v244
	s_waitcnt lgkmcnt(0)
	v_and_b32_e32 v81, 0xffff0000, v244
	v_lshlrev_b32_e32 v82, 16, v245
	v_and_b32_e32 v83, 0xffff0000, v245
	v_pk_fma_f32 v[78:79], v[78:79], 0.5, v[82:83] op_sel_hi:[1,0,1]
	v_pk_fma_f32 v[76:77], v[76:77], 0.5, v[80:81] op_sel_hi:[1,0,1]
	v_mul_f32_e32 v81, v79, v79
	v_mul_f32_e32 v80, v77, v77
	v_lshlrev_b32_e32 v84, 16, v246
	v_and_b32_e32 v85, 0xffff0000, v246
	v_lshlrev_b32_e32 v86, 16, v247
	v_and_b32_e32 v87, 0xffff0000, v247
	v_fmac_f32_e32 v80, v76, v76
	v_fmac_f32_e32 v81, v78, v78
	v_cvt_pk_bf16_f32 v232, v76, v77
	v_cvt_pk_bf16_f32 v233, v78, v79
	v_lshl_add_u64 v[78:79], s[34:35], 0, v[146:147]
	v_lshl_add_u64 v[78:79], v[140:141], 1, v[78:79]
	v_pk_fma_f32 v[74:75], v[74:75], 0.5, v[86:87] op_sel_hi:[1,0,1]
	v_pk_fma_f32 v[72:73], v[72:73], 0.5, v[84:85] op_sel_hi:[1,0,1]
	v_permlane16_swap_b32 v248, v250
	v_permlane16_swap_b32 v249, v251
	v_lshlrev_b32_e32 v88, 16, v248
	v_and_b32_e32 v89, 0xffff0000, v248
	v_lshlrev_b32_e32 v90, 16, v249
	v_and_b32_e32 v91, 0xffff0000, v249
	v_mul_f32_e32 v76, v73, v73
	v_mul_f32_e32 v77, v75, v75
	v_fmac_f32_e32 v76, v72, v72
	v_fmac_f32_e32 v77, v74, v74
	v_pk_fma_f32 v[70:71], v[70:71], 0.5, v[90:91] op_sel_hi:[1,0,1]
	v_pk_fma_f32 v[68:69], v[68:69], 0.5, v[88:89] op_sel_hi:[1,0,1]
	v_add_f32_e32 v76, v76, v77
	v_cvt_pk_bf16_f32 v234, v72, v73
	v_mul_f32_e32 v73, v69, v69
	v_mul_f32_e32 v77, v71, v71
	v_add_f32_e32 v80, v80, v81
	v_fmac_f32_e32 v73, v68, v68
	v_fmac_f32_e32 v77, v70, v70
	v_lshlrev_b32_e32 v92, 16, v250
	v_and_b32_e32 v93, 0xffff0000, v250
	v_lshlrev_b32_e32 v94, 16, v251
	v_and_b32_e32 v95, 0xffff0000, v251
	v_add_f32_e32 v76, v80, v76
	v_add_f32_e32 v73, v73, v77
	v_add_f32_e32 v73, v76, v73
	v_pk_fma_f32 v[66:67], v[66:67], 0.5, v[94:95] op_sel_hi:[1,0,1]
	v_pk_fma_f32 v[76:77], v[64:65], 0.5, v[92:93] op_sel_hi:[1,0,1]
	v_mul_f32_e32 v65, v67, v67
	v_mul_f32_e32 v64, v77, v77
	v_fmac_f32_e32 v64, v76, v76
	v_fmac_f32_e32 v65, v66, v66
	v_add_f32_e32 v64, v64, v65
	v_add_f32_e32 v64, v73, v64
	ds_bpermute_b32 v65, v178, v64
	v_cvt_pk_bf16_f32 v235, v74, v75
	s_nop 1
	v_permlane16_swap_b32 v232, v234
	v_permlane16_swap_b32 v233, v235
	v_lshl_add_u64 v[240:241], v[78:79], 0, v[242:243]
	global_store_dwordx4 v[240:241], v[232:235], off
	v_cvt_pk_bf16_f32 v236, v68, v69
	v_cvt_pk_bf16_f32 v237, v70, v71
	s_waitcnt lgkmcnt(0)
	v_add_f32_e32 v64, v64, v65
	ds_bpermute_b32 v65, v179, v64
	v_cvt_pk_bf16_f32 v238, v76, v77
	v_cvt_pk_bf16_f32 v239, v66, v67
	s_nop 1
	v_permlane16_swap_b32 v236, v238
	v_permlane16_swap_b32 v237, v239
	v_lshl_add_u64 v[240:241], v[78:79], 0, v[242:243]
	global_store_dwordx4 v[240:241], v[236:239], off offset:256
	s_and_saveexec_b64 s[50:51], s[6:7]
	s_cbranch_execz .LBB0_271
	s_waitcnt lgkmcnt(0)
	v_add_f32_e32 v64, v64, v65
	global_atomic_add_f32 v[112:113], v64, off offset:192
.LBB0_271:
	s_or_b64 exec, exec, s[50:51]
	s_mov_b64 s[50:51], 0x80000
	v_lshl_add_u64 v[94:95], v[144:145], 0, s[50:51]
	s_waitcnt lgkmcnt(0)
	v_lshl_add_u64 v[64:65], v[142:143], 0, v[94:95]
	v_lshl_add_u64 v[252:253], v[64:65], 0, v[242:243]
	global_load_dwordx4 v[208:211], v[252:253], off
	v_lshl_add_u64 v[252:253], v[64:65], 0, v[242:243]
	global_load_dwordx4 v[212:215], v[252:253], off offset:256
	s_mov_b64 s[50:51], 0x90000
	v_lshl_add_u64 v[74:75], v[144:145], 0, s[20:21]
	v_lshl_add_u64 v[64:65], v[144:145], 0, s[46:47]
	v_lshl_add_u64 v[84:85], v[144:145], 0, s[50:51]
	v_lshl_add_u64 v[66:67], v[142:143], 0, v[74:75]
	v_lshl_add_u64 v[86:87], v[142:143], 0, v[64:65]
	v_lshl_add_u64 v[104:105], v[142:143], 0, v[84:85]
	v_lshl_add_u64 v[252:253], v[66:67], 0, v[242:243]
	global_load_dwordx4 v[216:219], v[252:253], off
	v_lshl_add_u64 v[252:253], v[66:67], 0, v[242:243]
	global_load_dwordx4 v[220:223], v[252:253], off offset:256
	v_lshl_add_u64 v[252:253], v[86:87], 0, v[242:243]
	global_load_dwordx4 v[224:227], v[252:253], off
	v_lshl_add_u64 v[252:253], v[86:87], 0, v[242:243]
	global_load_dwordx4 v[228:231], v[252:253], off offset:256
	s_nop 0
	v_lshl_add_u64 v[252:253], v[104:105], 0, v[242:243]
	global_load_dwordx4 v[244:247], v[252:253], off
	v_lshl_add_u64 v[252:253], v[104:105], 0, v[242:243]
	global_load_dwordx4 v[248:251], v[252:253], off offset:256
	s_nop 0
	v_lshl_add_u64 v[94:95], s[34:35], 0, v[94:95]
	v_lshl_add_u64 v[94:95], v[140:141], 1, v[94:95]
	s_waitcnt vmcnt(7)
	v_permlane16_swap_b32 v208, v210
	v_permlane16_swap_b32 v209, v211
	v_lshlrev_b32_e32 v104, 16, v208
	v_and_b32_e32 v105, 0xffff0000, v208
	v_lshlrev_b32_e32 v96, 16, v209
	v_and_b32_e32 v97, 0xffff0000, v209
	s_waitcnt vmcnt(7)
	v_lshlrev_b32_e32 v106, 16, v210
	v_and_b32_e32 v107, 0xffff0000, v210
	v_lshlrev_b32_e32 v98, 16, v211
	v_and_b32_e32 v99, 0xffff0000, v211
	s_waitcnt vmcnt(6)
	v_permlane16_swap_b32 v212, v214
	v_permlane16_swap_b32 v213, v215
	v_lshlrev_b32_e32 v108, 16, v212
	v_and_b32_e32 v109, 0xffff0000, v212
	v_lshlrev_b32_e32 v100, 16, v213
	v_and_b32_e32 v101, 0xffff0000, v213
	s_waitcnt vmcnt(6)
	v_lshlrev_b32_e32 v110, 16, v214
	v_and_b32_e32 v111, 0xffff0000, v214
	v_pk_fma_f32 v[62:63], v[62:63], 0.5, v[96:97] op_sel_hi:[1,0,1]
	v_pk_fma_f32 v[60:61], v[60:61], 0.5, v[104:105] op_sel_hi:[1,0,1]
	v_pk_fma_f32 v[58:59], v[58:59], 0.5, v[98:99] op_sel_hi:[1,0,1]
	v_pk_fma_f32 v[56:57], v[56:57], 0.5, v[106:107] op_sel_hi:[1,0,1]
	v_lshlrev_b32_e32 v102, 16, v215
	v_and_b32_e32 v103, 0xffff0000, v215
	v_pk_fma_f32 v[54:55], v[54:55], 0.5, v[100:101] op_sel_hi:[1,0,1]
	v_pk_fma_f32 v[52:53], v[52:53], 0.5, v[108:109] op_sel_hi:[1,0,1]
	v_pk_fma_f32 v[96:97], v[48:49], 0.5, v[110:111] op_sel_hi:[1,0,1]
	v_mul_f32_e32 v98, v61, v61
	v_mul_f32_e32 v99, v63, v63
	v_cvt_pk_bf16_f32 v232, v60, v61
	v_cvt_pk_bf16_f32 v233, v62, v63
	v_mul_f32_e32 v61, v57, v57
	v_mul_f32_e32 v63, v59, v59
	v_pk_fma_f32 v[50:51], v[50:51], 0.5, v[102:103] op_sel_hi:[1,0,1]
	v_mul_f32_e32 v100, v53, v53
	v_mul_f32_e32 v101, v55, v55
	v_fmac_f32_e32 v98, v60, v60
	v_fmac_f32_e32 v99, v62, v62
	v_fmac_f32_e32 v61, v56, v56
	v_fmac_f32_e32 v63, v58, v58
	v_mul_f32_e32 v102, v97, v97
	v_mul_f32_e32 v103, v51, v51
	v_cvt_pk_bf16_f32 v234, v56, v57
	v_fmac_f32_e32 v100, v52, v52
	v_fmac_f32_e32 v101, v54, v54
	v_add_f32_e32 v49, v98, v99
	v_add_f32_e32 v56, v61, v63
	v_fmac_f32_e32 v102, v96, v96
	v_fmac_f32_e32 v103, v50, v50
	v_add_f32_e32 v57, v100, v101
	v_add_f32_e32 v49, v49, v56
	v_add_f32_e32 v49, v49, v57
	v_add_f32_e32 v56, v102, v103
	v_add_f32_e32 v56, v49, v56
	ds_bpermute_b32 v57, v178, v56
	v_cvt_pk_bf16_f32 v235, v58, v59
	s_nop 1
	v_permlane16_swap_b32 v232, v234
	v_permlane16_swap_b32 v233, v235
	v_lshl_add_u64 v[240:241], v[94:95], 0, v[242:243]
	global_store_dwordx4 v[240:241], v[232:235], off
	v_cvt_pk_bf16_f32 v236, v52, v53
	v_cvt_pk_bf16_f32 v237, v54, v55
	s_waitcnt lgkmcnt(0)
	v_add_f32_e32 v48, v56, v57
	ds_bpermute_b32 v49, v179, v48
	v_cvt_pk_bf16_f32 v238, v96, v97
	v_cvt_pk_bf16_f32 v239, v50, v51
	s_nop 1
	v_permlane16_swap_b32 v236, v238
	v_permlane16_swap_b32 v237, v239
	v_lshl_add_u64 v[240:241], v[94:95], 0, v[242:243]
	global_store_dwordx4 v[240:241], v[236:239], off offset:256
	s_and_saveexec_b64 s[50:51], s[6:7]
	s_cbranch_execz .LBB0_273
	s_waitcnt lgkmcnt(0)
	v_add_f32_e32 v48, v48, v49
	global_atomic_add_f32 v[112:113], v48, off offset:512
.LBB0_273:
	s_or_b64 exec, exec, s[50:51]
	s_waitcnt vmcnt(3)
	v_permlane16_swap_b32 v244, v246
	v_permlane16_swap_b32 v245, v247
	v_lshlrev_b32_e32 v48, 16, v244
	s_waitcnt lgkmcnt(0)
	v_and_b32_e32 v49, 0xffff0000, v244
	v_lshlrev_b32_e32 v50, 16, v245
	v_and_b32_e32 v51, 0xffff0000, v245
	v_pk_fma_f32 v[46:47], v[46:47], 0.5, v[50:51] op_sel_hi:[1,0,1]
	v_pk_fma_f32 v[44:45], v[44:45], 0.5, v[48:49] op_sel_hi:[1,0,1]
	v_mul_f32_e32 v49, v47, v47
	v_mul_f32_e32 v48, v45, v45
	s_waitcnt vmcnt(3)
	v_lshlrev_b32_e32 v52, 16, v246
	v_and_b32_e32 v53, 0xffff0000, v246
	v_lshlrev_b32_e32 v54, 16, v247
	v_and_b32_e32 v55, 0xffff0000, v247
	v_fmac_f32_e32 v48, v44, v44
	v_fmac_f32_e32 v49, v46, v46
	v_cvt_pk_bf16_f32 v232, v44, v45
	v_cvt_pk_bf16_f32 v233, v46, v47
	v_lshl_add_u64 v[46:47], s[34:35], 0, v[84:85]
	v_lshl_add_u64 v[46:47], v[140:141], 1, v[46:47]
	v_pk_fma_f32 v[42:43], v[42:43], 0.5, v[54:55] op_sel_hi:[1,0,1]
	v_pk_fma_f32 v[40:41], v[40:41], 0.5, v[52:53] op_sel_hi:[1,0,1]
	s_waitcnt vmcnt(2)
	v_permlane16_swap_b32 v248, v250
	v_permlane16_swap_b32 v249, v251
	v_lshlrev_b32_e32 v56, 16, v248
	v_and_b32_e32 v57, 0xffff0000, v248
	v_lshlrev_b32_e32 v58, 16, v249
	v_and_b32_e32 v59, 0xffff0000, v249
	v_mul_f32_e32 v44, v41, v41
	v_mul_f32_e32 v45, v43, v43
	v_fmac_f32_e32 v44, v40, v40
	v_fmac_f32_e32 v45, v42, v42
	v_pk_fma_f32 v[38:39], v[38:39], 0.5, v[58:59] op_sel_hi:[1,0,1]
	v_pk_fma_f32 v[36:37], v[36:37], 0.5, v[56:57] op_sel_hi:[1,0,1]
	v_add_f32_e32 v44, v44, v45
	v_cvt_pk_bf16_f32 v234, v40, v41
	v_mul_f32_e32 v41, v37, v37
	v_mul_f32_e32 v45, v39, v39
	v_add_f32_e32 v48, v48, v49
	v_fmac_f32_e32 v41, v36, v36
	v_fmac_f32_e32 v45, v38, v38
	s_waitcnt vmcnt(2)
	v_lshlrev_b32_e32 v60, 16, v250
	v_and_b32_e32 v61, 0xffff0000, v250
	v_lshlrev_b32_e32 v62, 16, v251
	v_and_b32_e32 v63, 0xffff0000, v251
	v_add_f32_e32 v44, v48, v44
	v_add_f32_e32 v41, v41, v45
	v_add_f32_e32 v41, v44, v41
	v_pk_fma_f32 v[34:35], v[34:35], 0.5, v[62:63] op_sel_hi:[1,0,1]
	v_pk_fma_f32 v[44:45], v[32:33], 0.5, v[60:61] op_sel_hi:[1,0,1]
	v_mul_f32_e32 v33, v35, v35
	v_mul_f32_e32 v32, v45, v45
	v_fmac_f32_e32 v32, v44, v44
	v_fmac_f32_e32 v33, v34, v34
	v_add_f32_e32 v32, v32, v33
	v_add_f32_e32 v32, v41, v32
	ds_bpermute_b32 v33, v178, v32
	v_cvt_pk_bf16_f32 v235, v42, v43
	s_nop 1
	v_permlane16_swap_b32 v232, v234
	v_permlane16_swap_b32 v233, v235
	v_lshl_add_u64 v[240:241], v[46:47], 0, v[242:243]
	global_store_dwordx4 v[240:241], v[232:235], off
	v_cvt_pk_bf16_f32 v236, v36, v37
	v_cvt_pk_bf16_f32 v237, v38, v39
	s_waitcnt lgkmcnt(0)
	v_add_f32_e32 v32, v32, v33
	ds_bpermute_b32 v33, v179, v32
	v_cvt_pk_bf16_f32 v238, v44, v45
	v_cvt_pk_bf16_f32 v239, v34, v35
	s_nop 1
	v_permlane16_swap_b32 v236, v238
	v_permlane16_swap_b32 v237, v239
	v_lshl_add_u64 v[240:241], v[46:47], 0, v[242:243]
	global_store_dwordx4 v[240:241], v[236:239], off offset:256
	s_and_saveexec_b64 s[50:51], s[6:7]
	s_cbranch_execz .LBB0_275
	s_waitcnt lgkmcnt(0)
	v_add_f32_e32 v32, v32, v33
	global_atomic_add_f32 v[112:113], v32, off offset:576
.LBB0_275:
	s_or_b64 exec, exec, s[50:51]
	v_permlane16_swap_b32 v216, v218
	v_permlane16_swap_b32 v217, v219
	v_lshlrev_b32_e32 v32, 16, v216
	s_waitcnt lgkmcnt(0)
	v_and_b32_e32 v33, 0xffff0000, v216
	v_lshlrev_b32_e32 v34, 16, v217
	v_and_b32_e32 v35, 0xffff0000, v217
	v_pk_fma_f32 v[30:31], v[30:31], 0.5, v[34:35] op_sel_hi:[1,0,1]
	v_pk_fma_f32 v[28:29], v[28:29], 0.5, v[32:33] op_sel_hi:[1,0,1]
	v_mul_f32_e32 v33, v31, v31
	v_mul_f32_e32 v32, v29, v29
	v_lshlrev_b32_e32 v36, 16, v218
	v_and_b32_e32 v37, 0xffff0000, v218
	v_lshlrev_b32_e32 v38, 16, v219
	v_and_b32_e32 v39, 0xffff0000, v219
	v_fmac_f32_e32 v32, v28, v28
	v_fmac_f32_e32 v33, v30, v30
	v_cvt_pk_bf16_f32 v232, v28, v29
	v_cvt_pk_bf16_f32 v233, v30, v31
	v_lshl_add_u64 v[30:31], s[34:35], 0, v[74:75]
	v_lshl_add_u64 v[30:31], v[140:141], 1, v[30:31]
	v_pk_fma_f32 v[26:27], v[26:27], 0.5, v[38:39] op_sel_hi:[1,0,1]
	v_pk_fma_f32 v[24:25], v[24:25], 0.5, v[36:37] op_sel_hi:[1,0,1]
	v_permlane16_swap_b32 v220, v222
	v_permlane16_swap_b32 v221, v223
	v_lshlrev_b32_e32 v40, 16, v220
	v_and_b32_e32 v41, 0xffff0000, v220
	v_lshlrev_b32_e32 v42, 16, v221
	v_and_b32_e32 v43, 0xffff0000, v221
	v_mul_f32_e32 v28, v25, v25
	v_mul_f32_e32 v29, v27, v27
	v_fmac_f32_e32 v28, v24, v24
	v_fmac_f32_e32 v29, v26, v26
	v_pk_fma_f32 v[22:23], v[22:23], 0.5, v[42:43] op_sel_hi:[1,0,1]
	v_pk_fma_f32 v[20:21], v[20:21], 0.5, v[40:41] op_sel_hi:[1,0,1]
	v_add_f32_e32 v28, v28, v29
	v_cvt_pk_bf16_f32 v234, v24, v25
	v_mul_f32_e32 v25, v21, v21
	v_mul_f32_e32 v29, v23, v23
	v_add_f32_e32 v32, v32, v33
	v_fmac_f32_e32 v25, v20, v20
	v_fmac_f32_e32 v29, v22, v22
	v_lshlrev_b32_e32 v44, 16, v222
	v_and_b32_e32 v45, 0xffff0000, v222
	v_lshlrev_b32_e32 v46, 16, v223
	v_and_b32_e32 v47, 0xffff0000, v223
	v_add_f32_e32 v28, v32, v28
	v_add_f32_e32 v25, v25, v29
	v_add_f32_e32 v25, v28, v25
	v_pk_fma_f32 v[18:19], v[18:19], 0.5, v[46:47] op_sel_hi:[1,0,1]
	v_pk_fma_f32 v[28:29], v[16:17], 0.5, v[44:45] op_sel_hi:[1,0,1]
	v_mul_f32_e32 v17, v19, v19
	v_mul_f32_e32 v16, v29, v29
	v_fmac_f32_e32 v16, v28, v28
	v_fmac_f32_e32 v17, v18, v18
	v_add_f32_e32 v16, v16, v17
	v_add_f32_e32 v16, v25, v16
	ds_bpermute_b32 v17, v178, v16
	v_cvt_pk_bf16_f32 v235, v26, v27
	s_nop 1
	v_permlane16_swap_b32 v232, v234
	v_permlane16_swap_b32 v233, v235
	v_lshl_add_u64 v[240:241], v[30:31], 0, v[242:243]
	global_store_dwordx4 v[240:241], v[232:235], off
	v_cvt_pk_bf16_f32 v236, v20, v21
	v_cvt_pk_bf16_f32 v237, v22, v23
	s_waitcnt lgkmcnt(0)
	v_add_f32_e32 v16, v16, v17
	ds_bpermute_b32 v17, v179, v16
	v_cvt_pk_bf16_f32 v238, v28, v29
	v_cvt_pk_bf16_f32 v239, v18, v19
	s_nop 1
	v_permlane16_swap_b32 v236, v238
	v_permlane16_swap_b32 v237, v239
	v_lshl_add_u64 v[240:241], v[30:31], 0, v[242:243]
	global_store_dwordx4 v[240:241], v[236:239], off offset:256
	s_and_saveexec_b64 s[50:51], s[6:7]
	s_cbranch_execz .LBB0_277
	s_waitcnt lgkmcnt(0)
	v_add_f32_e32 v16, v16, v17
	global_atomic_add_f32 v[112:113], v16, off offset:640
.LBB0_277:
	s_or_b64 exec, exec, s[50:51]
	v_permlane16_swap_b32 v224, v226
	v_permlane16_swap_b32 v225, v227
	v_lshlrev_b32_e32 v16, 16, v224
	s_waitcnt lgkmcnt(0)
	v_and_b32_e32 v17, 0xffff0000, v224
	v_lshlrev_b32_e32 v18, 16, v225
	v_and_b32_e32 v19, 0xffff0000, v225
	v_pk_fma_f32 v[14:15], v[14:15], 0.5, v[18:19] op_sel_hi:[1,0,1]
	v_pk_fma_f32 v[12:13], v[12:13], 0.5, v[16:17] op_sel_hi:[1,0,1]
	v_mul_f32_e32 v17, v15, v15
	v_mul_f32_e32 v16, v13, v13
	v_lshlrev_b32_e32 v20, 16, v226
	v_and_b32_e32 v21, 0xffff0000, v226
	v_lshlrev_b32_e32 v22, 16, v227
	v_and_b32_e32 v23, 0xffff0000, v227
	v_fmac_f32_e32 v16, v12, v12
	v_fmac_f32_e32 v17, v14, v14
	v_cvt_pk_bf16_f32 v232, v12, v13
	v_cvt_pk_bf16_f32 v233, v14, v15
	v_lshl_add_u64 v[14:15], s[34:35], 0, v[64:65]
	v_lshl_add_u64 v[14:15], v[140:141], 1, v[14:15]
	v_pk_fma_f32 v[10:11], v[10:11], 0.5, v[22:23] op_sel_hi:[1,0,1]
	v_pk_fma_f32 v[8:9], v[8:9], 0.5, v[20:21] op_sel_hi:[1,0,1]
	v_permlane16_swap_b32 v228, v230
	v_permlane16_swap_b32 v229, v231
	v_lshlrev_b32_e32 v24, 16, v228
	v_and_b32_e32 v25, 0xffff0000, v228
	v_lshlrev_b32_e32 v26, 16, v229
	v_and_b32_e32 v27, 0xffff0000, v229
	v_mul_f32_e32 v12, v9, v9
	v_mul_f32_e32 v13, v11, v11
	v_fmac_f32_e32 v12, v8, v8
	v_fmac_f32_e32 v13, v10, v10
	v_pk_fma_f32 v[6:7], v[6:7], 0.5, v[26:27] op_sel_hi:[1,0,1]
	v_pk_fma_f32 v[4:5], v[4:5], 0.5, v[24:25] op_sel_hi:[1,0,1]
	v_add_f32_e32 v12, v12, v13
	v_cvt_pk_bf16_f32 v234, v8, v9
	v_mul_f32_e32 v9, v5, v5
	v_mul_f32_e32 v13, v7, v7
	v_add_f32_e32 v16, v16, v17
	v_fmac_f32_e32 v9, v4, v4
	v_fmac_f32_e32 v13, v6, v6
	v_lshlrev_b32_e32 v28, 16, v230
	v_and_b32_e32 v29, 0xffff0000, v230
	v_lshlrev_b32_e32 v30, 16, v231
	v_and_b32_e32 v31, 0xffff0000, v231
	v_add_f32_e32 v12, v16, v12
	v_add_f32_e32 v9, v9, v13
	v_add_f32_e32 v9, v12, v9
	v_pk_fma_f32 v[2:3], v[2:3], 0.5, v[30:31] op_sel_hi:[1,0,1]
	v_pk_fma_f32 v[12:13], v[0:1], 0.5, v[28:29] op_sel_hi:[1,0,1]
	v_mul_f32_e32 v1, v3, v3
	v_mul_f32_e32 v0, v13, v13
	v_fmac_f32_e32 v0, v12, v12
	v_fmac_f32_e32 v1, v2, v2
	v_add_f32_e32 v0, v0, v1
	v_add_f32_e32 v0, v9, v0
	ds_bpermute_b32 v1, v178, v0
	v_cvt_pk_bf16_f32 v235, v10, v11
	s_nop 1
	v_permlane16_swap_b32 v232, v234
	v_permlane16_swap_b32 v233, v235
	v_lshl_add_u64 v[240:241], v[14:15], 0, v[242:243]
	global_store_dwordx4 v[240:241], v[232:235], off
	v_cvt_pk_bf16_f32 v236, v4, v5
	v_cvt_pk_bf16_f32 v237, v6, v7
	s_waitcnt lgkmcnt(0)
	v_add_f32_e32 v0, v0, v1
	ds_bpermute_b32 v1, v179, v0
	v_cvt_pk_bf16_f32 v238, v12, v13
	v_cvt_pk_bf16_f32 v239, v2, v3
	s_nop 1
	v_permlane16_swap_b32 v236, v238
	v_permlane16_swap_b32 v237, v239
	v_lshl_add_u64 v[240:241], v[14:15], 0, v[242:243]
	global_store_dwordx4 v[240:241], v[236:239], off offset:256
	s_and_saveexec_b64 s[50:51], s[6:7]
	s_cbranch_execz .LBB0_279
	s_waitcnt lgkmcnt(0)
	v_add_f32_e32 v0, v0, v1
	global_atomic_add_f32 v[112:113], v0, off offset:704

.LBB0_753:
	v_mbcnt_lo_u32_b32 v242, -1, 0
	v_mbcnt_hi_u32_b32 v242, -1, v242
	v_bfe_u32 v242, v242, 4, 1
	v_mul_u32_u24_e32 v242, 24, v242
	v_mov_b32_e32 v243, 0
	v_lshl_or_b32 v140, s42, 8, v186
	v_lshl_add_u32 v144, s40, 8, v182
	v_ashrrev_i32_e32 v141, 31, v140
	v_lshlrev_b64 v[190:191], 1, v[140:141]
	v_ashrrev_i32_e32 v145, 31, v144
	v_lshl_add_u64 v[142:143], s[34:35], 0, v[190:191]
	v_lshlrev_b64 v[192:193], 12, v[144:145]
	v_lshl_add_u64 v[146:147], v[142:143], 0, v[192:193]
	v_lshl_add_u64 v[252:253], v[146:147], 0, v[242:243]
	global_load_dwordx4 v[208:211], v[252:253], off
	v_lshl_add_u64 v[252:253], v[146:147], 0, v[242:243]
	global_load_dwordx4 v[212:215], v[252:253], off offset:256
	v_or_b32_e32 v162, 16, v144
	v_or_b32_e32 v150, 32, v144
	v_or_b32_e32 v146, 48, v144
	v_ashrrev_i32_e32 v163, 31, v162
	v_ashrrev_i32_e32 v151, 31, v150
	v_ashrrev_i32_e32 v147, 31, v146
	v_lshlrev_b64 v[172:173], 12, v[162:163]
	v_lshlrev_b64 v[160:161], 12, v[150:151]
	v_lshlrev_b64 v[148:149], 12, v[146:147]
	v_lshl_add_u64 v[152:153], v[142:143], 0, v[172:173]
	v_lshl_add_u64 v[154:155], v[142:143], 0, v[160:161]
	v_lshl_add_u64 v[202:203], v[142:143], 0, v[148:149]
	v_lshl_add_u64 v[252:253], v[152:153], 0, v[242:243]
	global_load_dwordx4 v[216:219], v[252:253], off
	v_lshl_add_u64 v[252:253], v[152:153], 0, v[242:243]
	global_load_dwordx4 v[220:223], v[252:253], off offset:256
	v_lshl_add_u64 v[252:253], v[154:155], 0, v[242:243]
	global_load_dwordx4 v[224:227], v[252:253], off
	v_lshl_add_u64 v[252:253], v[154:155], 0, v[242:243]
	global_load_dwordx4 v[228:231], v[252:253], off offset:256
	v_lshl_add_u64 v[252:253], v[202:203], 0, v[242:243]
	global_load_dwordx4 v[244:247], v[252:253], off
	s_nop 0
	v_lshl_add_u64 v[252:253], v[202:203], 0, v[242:243]
	global_load_dwordx4 v[248:251], v[252:253], off offset:256
	v_lshl_add_u64 v[192:193], s[34:35], 0, v[192:193]
	v_lshl_add_u64 v[190:191], v[192:193], 0, v[190:191]
	s_waitcnt vmcnt(0)
	v_permlane16_swap_b32 v208, v210
	v_permlane16_swap_b32 v209, v211
	v_lshlrev_b32_e32 v192, 16, v208
	v_and_b32_e32 v193, 0xffff0000, v208
	v_lshlrev_b32_e32 v194, 16, v209
	v_and_b32_e32 v195, 0xffff0000, v209
	v_lshlrev_b32_e32 v202, 16, v210
	v_and_b32_e32 v203, 0xffff0000, v210
	v_lshlrev_b32_e32 v196, 16, v211
	v_and_b32_e32 v197, 0xffff0000, v211
	v_permlane16_swap_b32 v212, v214
	v_permlane16_swap_b32 v213, v215
	v_lshlrev_b32_e32 v204, 16, v212
	v_and_b32_e32 v205, 0xffff0000, v212
	v_lshlrev_b32_e32 v198, 16, v213
	v_and_b32_e32 v199, 0xffff0000, v213
	v_lshlrev_b32_e32 v206, 16, v214
	v_and_b32_e32 v207, 0xffff0000, v214
	v_pk_add_f32 v[126:127], v[126:127], v[194:195]
	v_pk_add_f32 v[124:125], v[124:125], v[192:193]
	v_pk_add_f32 v[122:123], v[122:123], v[196:197]
	v_pk_add_f32 v[120:121], v[120:121], v[202:203]
	v_lshlrev_b32_e32 v200, 16, v215
	v_and_b32_e32 v201, 0xffff0000, v215
	v_pk_add_f32 v[118:119], v[118:119], v[198:199]
	v_pk_add_f32 v[116:117], v[116:117], v[204:205]
	v_pk_add_f32 v[192:193], v[112:113], v[206:207]
	v_mul_f32_e32 v194, v125, v125
	v_mul_f32_e32 v195, v127, v127
	v_cvt_pk_bf16_f32 v232, v124, v125
	v_cvt_pk_bf16_f32 v233, v126, v127
	v_mul_f32_e32 v125, v121, v121
	v_mul_f32_e32 v127, v123, v123
	v_pk_add_f32 v[114:115], v[114:115], v[200:201]
	v_mul_f32_e32 v196, v117, v117
	v_mul_f32_e32 v197, v119, v119
	v_fmac_f32_e32 v194, v124, v124
	v_fmac_f32_e32 v195, v126, v126
	v_fmac_f32_e32 v125, v120, v120
	v_fmac_f32_e32 v127, v122, v122
	v_mul_f32_e32 v198, v193, v193
	v_mul_f32_e32 v199, v115, v115
	v_cvt_pk_bf16_f32 v234, v120, v121
	v_fmac_f32_e32 v196, v116, v116
	v_fmac_f32_e32 v197, v118, v118
	v_add_f32_e32 v113, v194, v195
	v_add_f32_e32 v120, v125, v127
	v_fmac_f32_e32 v198, v192, v192
	v_fmac_f32_e32 v199, v114, v114
	v_add_f32_e32 v121, v196, v197
	v_add_f32_e32 v113, v113, v120
	v_add_f32_e32 v113, v113, v121
	v_add_f32_e32 v120, v198, v199
	v_add_f32_e32 v120, v113, v120
	ds_bpermute_b32 v121, v184, v120
	v_cvt_pk_bf16_f32 v235, v122, v123
	s_nop 1
	v_permlane16_swap_b32 v232, v234
	v_permlane16_swap_b32 v233, v235
	v_lshl_add_u64 v[240:241], v[190:191], 0, v[242:243]
	global_store_dwordx4 v[240:241], v[232:235], off
	v_cvt_pk_bf16_f32 v236, v116, v117
	v_cvt_pk_bf16_f32 v237, v118, v119
	s_waitcnt lgkmcnt(0)
	v_add_f32_e32 v112, v120, v121
	ds_bpermute_b32 v113, v185, v112
	v_cvt_pk_bf16_f32 v238, v192, v193
	v_cvt_pk_bf16_f32 v239, v114, v115
	s_nop 1
	v_permlane16_swap_b32 v236, v238
	v_permlane16_swap_b32 v237, v239
	v_lshl_add_u64 v[240:241], v[190:191], 0, v[242:243]
	global_store_dwordx4 v[240:241], v[236:239], off offset:256
	s_and_saveexec_b64 s[40:41], s[8:9]
	s_cbranch_execz .LBB0_755
	v_lshl_add_u64 v[114:115], v[144:145], 2, s[12:13]
	s_waitcnt lgkmcnt(0)
	v_add_f32_e32 v112, v112, v113
	global_atomic_add_f32 v[114:115], v112, off
.LBB0_755:
	s_or_b64 exec, exec, s[40:41]
	v_permlane16_swap_b32 v216, v218
	v_permlane16_swap_b32 v217, v219
	v_lshlrev_b32_e32 v112, 16, v216
	s_waitcnt lgkmcnt(0)
	v_and_b32_e32 v113, 0xffff0000, v216
	v_lshlrev_b32_e32 v114, 16, v217
	v_and_b32_e32 v115, 0xffff0000, v217
	v_pk_add_f32 v[110:111], v[110:111], v[114:115]
	v_pk_add_f32 v[108:109], v[108:109], v[112:113]
	v_mul_f32_e32 v113, v111, v111
	v_mul_f32_e32 v112, v109, v109
	v_lshlrev_b32_e32 v116, 16, v218
	v_and_b32_e32 v117, 0xffff0000, v218
	v_lshlrev_b32_e32 v118, 16, v219
	v_and_b32_e32 v119, 0xffff0000, v219
	v_fmac_f32_e32 v112, v108, v108
	v_fmac_f32_e32 v113, v110, v110
	v_cvt_pk_bf16_f32 v232, v108, v109
	v_cvt_pk_bf16_f32 v233, v110, v111
	v_lshl_add_u64 v[110:111], s[34:35], 0, v[172:173]
	v_lshl_add_u64 v[110:111], v[140:141], 1, v[110:111]
	v_pk_add_f32 v[106:107], v[106:107], v[118:119]
	v_pk_add_f32 v[104:105], v[104:105], v[116:117]
	v_permlane16_swap_b32 v220, v222
	v_permlane16_swap_b32 v221, v223
	v_lshlrev_b32_e32 v120, 16, v220
	v_and_b32_e32 v121, 0xffff0000, v220
	v_lshlrev_b32_e32 v122, 16, v221
	v_and_b32_e32 v123, 0xffff0000, v221
	v_mul_f32_e32 v108, v105, v105
	v_mul_f32_e32 v109, v107, v107
	v_fmac_f32_e32 v108, v104, v104
	v_fmac_f32_e32 v109, v106, v106
	v_pk_add_f32 v[102:103], v[102:103], v[122:123]
	v_pk_add_f32 v[100:101], v[100:101], v[120:121]
	v_add_f32_e32 v108, v108, v109
	v_cvt_pk_bf16_f32 v234, v104, v105
	v_mul_f32_e32 v105, v101, v101
	v_mul_f32_e32 v109, v103, v103
	v_add_f32_e32 v112, v112, v113
	v_fmac_f32_e32 v105, v100, v100
	v_fmac_f32_e32 v109, v102, v102
	v_lshlrev_b32_e32 v124, 16, v222
	v_and_b32_e32 v125, 0xffff0000, v222
	v_lshlrev_b32_e32 v126, 16, v223
	v_and_b32_e32 v127, 0xffff0000, v223
	v_add_f32_e32 v108, v112, v108
	v_add_f32_e32 v105, v105, v109
	v_add_f32_e32 v105, v108, v105
	v_pk_add_f32 v[98:99], v[98:99], v[126:127]
	v_pk_add_f32 v[108:109], v[96:97], v[124:125]
	v_mul_f32_e32 v97, v99, v99
	v_mul_f32_e32 v96, v109, v109
	v_fmac_f32_e32 v96, v108, v108
	v_fmac_f32_e32 v97, v98, v98
	v_add_f32_e32 v96, v96, v97
	v_add_f32_e32 v96, v105, v96
	ds_bpermute_b32 v97, v184, v96
	v_cvt_pk_bf16_f32 v235, v106, v107
	s_nop 1
	v_permlane16_swap_b32 v232, v234
	v_permlane16_swap_b32 v233, v235
	v_lshl_add_u64 v[240:241], v[110:111], 0, v[242:243]
	global_store_dwordx4 v[240:241], v[232:235], off
	v_cvt_pk_bf16_f32 v236, v100, v101
	v_cvt_pk_bf16_f32 v237, v102, v103
	s_waitcnt lgkmcnt(0)
	v_add_f32_e32 v96, v96, v97
	ds_bpermute_b32 v97, v185, v96
	v_cvt_pk_bf16_f32 v238, v108, v109
	v_cvt_pk_bf16_f32 v239, v98, v99
	s_nop 1
	v_permlane16_swap_b32 v236, v238
	v_permlane16_swap_b32 v237, v239
	v_lshl_add_u64 v[240:241], v[110:111], 0, v[242:243]
	global_store_dwordx4 v[240:241], v[236:239], off offset:256
	s_and_saveexec_b64 s[40:41], s[8:9]
	s_cbranch_execz .LBB0_757
	v_lshl_add_u64 v[98:99], v[162:163], 2, s[12:13]
	s_waitcnt lgkmcnt(0)
	v_add_f32_e32 v96, v96, v97
	global_atomic_add_f32 v[98:99], v96, off
.LBB0_757:
	s_or_b64 exec, exec, s[40:41]
	v_permlane16_swap_b32 v224, v226
	v_permlane16_swap_b32 v225, v227
	v_lshlrev_b32_e32 v96, 16, v224
	s_waitcnt lgkmcnt(0)
	v_and_b32_e32 v97, 0xffff0000, v224
	v_lshlrev_b32_e32 v98, 16, v225
	v_and_b32_e32 v99, 0xffff0000, v225
	v_pk_add_f32 v[94:95], v[94:95], v[98:99]
	v_pk_add_f32 v[92:93], v[92:93], v[96:97]
	v_mul_f32_e32 v97, v95, v95
	v_mul_f32_e32 v96, v93, v93
	v_lshlrev_b32_e32 v100, 16, v226
	v_and_b32_e32 v101, 0xffff0000, v226
	v_lshlrev_b32_e32 v102, 16, v227
	v_and_b32_e32 v103, 0xffff0000, v227
	v_fmac_f32_e32 v96, v92, v92
	v_fmac_f32_e32 v97, v94, v94
	v_cvt_pk_bf16_f32 v232, v92, v93
	v_cvt_pk_bf16_f32 v233, v94, v95
	v_lshl_add_u64 v[94:95], s[34:35], 0, v[160:161]
	v_lshl_add_u64 v[94:95], v[140:141], 1, v[94:95]
	v_pk_add_f32 v[90:91], v[90:91], v[102:103]
	v_pk_add_f32 v[88:89], v[88:89], v[100:101]
	v_permlane16_swap_b32 v228, v230
	v_permlane16_swap_b32 v229, v231
	v_lshlrev_b32_e32 v104, 16, v228
	v_and_b32_e32 v105, 0xffff0000, v228
	v_lshlrev_b32_e32 v106, 16, v229
	v_and_b32_e32 v107, 0xffff0000, v229
	v_mul_f32_e32 v92, v89, v89
	v_mul_f32_e32 v93, v91, v91
	v_fmac_f32_e32 v92, v88, v88
	v_fmac_f32_e32 v93, v90, v90
	v_pk_add_f32 v[86:87], v[86:87], v[106:107]
	v_pk_add_f32 v[84:85], v[84:85], v[104:105]
	v_add_f32_e32 v92, v92, v93
	v_cvt_pk_bf16_f32 v234, v88, v89
	v_mul_f32_e32 v89, v85, v85
	v_mul_f32_e32 v93, v87, v87
	v_add_f32_e32 v96, v96, v97
	v_fmac_f32_e32 v89, v84, v84
	v_fmac_f32_e32 v93, v86, v86
	v_lshlrev_b32_e32 v108, 16, v230
	v_and_b32_e32 v109, 0xffff0000, v230
	v_lshlrev_b32_e32 v110, 16, v231
	v_and_b32_e32 v111, 0xffff0000, v231
	v_add_f32_e32 v92, v96, v92
	v_add_f32_e32 v89, v89, v93
	v_add_f32_e32 v89, v92, v89
	v_pk_add_f32 v[82:83], v[82:83], v[110:111]
	v_pk_add_f32 v[92:93], v[80:81], v[108:109]
	v_mul_f32_e32 v81, v83, v83
	v_mul_f32_e32 v80, v93, v93
	v_fmac_f32_e32 v80, v92, v92
	v_fmac_f32_e32 v81, v82, v82
	v_add_f32_e32 v80, v80, v81
	v_add_f32_e32 v80, v89, v80
	ds_bpermute_b32 v81, v184, v80
	v_cvt_pk_bf16_f32 v235, v90, v91
	s_nop 1
	v_permlane16_swap_b32 v232, v234
	v_permlane16_swap_b32 v233, v235
	v_lshl_add_u64 v[240:241], v[94:95], 0, v[242:243]
	global_store_dwordx4 v[240:241], v[232:235], off
	v_cvt_pk_bf16_f32 v236, v84, v85
	v_cvt_pk_bf16_f32 v237, v86, v87
	s_waitcnt lgkmcnt(0)
	v_add_f32_e32 v80, v80, v81
	ds_bpermute_b32 v81, v185, v80
	v_cvt_pk_bf16_f32 v238, v92, v93
	v_cvt_pk_bf16_f32 v239, v82, v83
	s_nop 1
	v_permlane16_swap_b32 v236, v238
	v_permlane16_swap_b32 v237, v239
	v_lshl_add_u64 v[240:241], v[94:95], 0, v[242:243]
	global_store_dwordx4 v[240:241], v[236:239], off offset:256
	s_and_saveexec_b64 s[40:41], s[8:9]
	s_cbranch_execz .LBB0_759
	v_lshl_add_u64 v[82:83], v[150:151], 2, s[12:13]
	s_waitcnt lgkmcnt(0)
	v_add_f32_e32 v80, v80, v81
	global_atomic_add_f32 v[82:83], v80, off
.LBB0_759:
	s_or_b64 exec, exec, s[40:41]
	v_permlane16_swap_b32 v244, v246
	v_permlane16_swap_b32 v245, v247
	v_lshlrev_b32_e32 v80, 16, v244
	s_waitcnt lgkmcnt(0)
	v_and_b32_e32 v81, 0xffff0000, v244
	v_lshlrev_b32_e32 v82, 16, v245
	v_and_b32_e32 v83, 0xffff0000, v245
	v_pk_add_f32 v[78:79], v[78:79], v[82:83]
	v_pk_add_f32 v[76:77], v[76:77], v[80:81]
	v_mul_f32_e32 v81, v79, v79
	v_mul_f32_e32 v80, v77, v77
	v_lshlrev_b32_e32 v84, 16, v246
	v_and_b32_e32 v85, 0xffff0000, v246
	v_lshlrev_b32_e32 v86, 16, v247
	v_and_b32_e32 v87, 0xffff0000, v247
	v_fmac_f32_e32 v80, v76, v76
	v_fmac_f32_e32 v81, v78, v78
	v_cvt_pk_bf16_f32 v232, v76, v77
	v_cvt_pk_bf16_f32 v233, v78, v79
	v_lshl_add_u64 v[78:79], s[34:35], 0, v[148:149]
	v_lshl_add_u64 v[78:79], v[140:141], 1, v[78:79]
	v_pk_add_f32 v[74:75], v[74:75], v[86:87]
	v_pk_add_f32 v[72:73], v[72:73], v[84:85]
	v_permlane16_swap_b32 v248, v250
	v_permlane16_swap_b32 v249, v251
	v_lshlrev_b32_e32 v88, 16, v248
	v_and_b32_e32 v89, 0xffff0000, v248
	v_lshlrev_b32_e32 v90, 16, v249
	v_and_b32_e32 v91, 0xffff0000, v249
	v_mul_f32_e32 v76, v73, v73
	v_mul_f32_e32 v77, v75, v75
	v_fmac_f32_e32 v76, v72, v72
	v_fmac_f32_e32 v77, v74, v74
	v_pk_add_f32 v[70:71], v[70:71], v[90:91]
	v_pk_add_f32 v[68:69], v[68:69], v[88:89]
	v_add_f32_e32 v76, v76, v77
	v_cvt_pk_bf16_f32 v234, v72, v73
	v_mul_f32_e32 v73, v69, v69
	v_mul_f32_e32 v77, v71, v71
	v_add_f32_e32 v80, v80, v81
	v_fmac_f32_e32 v73, v68, v68
	v_fmac_f32_e32 v77, v70, v70
	v_lshlrev_b32_e32 v92, 16, v250
	v_and_b32_e32 v93, 0xffff0000, v250
	v_lshlrev_b32_e32 v94, 16, v251
	v_and_b32_e32 v95, 0xffff0000, v251
	v_add_f32_e32 v76, v80, v76
	v_add_f32_e32 v73, v73, v77
	v_add_f32_e32 v73, v76, v73
	v_pk_add_f32 v[66:67], v[66:67], v[94:95]
	v_pk_add_f32 v[76:77], v[64:65], v[92:93]
	v_mul_f32_e32 v65, v67, v67
	v_mul_f32_e32 v64, v77, v77
	v_fmac_f32_e32 v64, v76, v76
	v_fmac_f32_e32 v65, v66, v66
	v_add_f32_e32 v64, v64, v65
	v_add_f32_e32 v64, v73, v64
	ds_bpermute_b32 v65, v184, v64
	v_cvt_pk_bf16_f32 v235, v74, v75
	s_nop 1
	v_permlane16_swap_b32 v232, v234
	v_permlane16_swap_b32 v233, v235
	v_lshl_add_u64 v[240:241], v[78:79], 0, v[242:243]
	global_store_dwordx4 v[240:241], v[232:235], off
	v_cvt_pk_bf16_f32 v236, v68, v69
	v_cvt_pk_bf16_f32 v237, v70, v71
	s_waitcnt lgkmcnt(0)
	v_add_f32_e32 v64, v64, v65
	ds_bpermute_b32 v65, v185, v64
	v_cvt_pk_bf16_f32 v238, v76, v77
	v_cvt_pk_bf16_f32 v239, v66, v67
	s_nop 1
	v_permlane16_swap_b32 v236, v238
	v_permlane16_swap_b32 v237, v239
	v_lshl_add_u64 v[240:241], v[78:79], 0, v[242:243]
	global_store_dwordx4 v[240:241], v[236:239], off offset:256
	s_and_saveexec_b64 s[40:41], s[8:9]
	s_cbranch_execz .LBB0_761
	v_lshl_add_u64 v[66:67], v[146:147], 2, s[12:13]
	s_waitcnt lgkmcnt(0)
	v_add_f32_e32 v64, v64, v65
	global_atomic_add_f32 v[66:67], v64, off
.LBB0_761:
	s_or_b64 exec, exec, s[40:41]
	v_add_u32_e32 v90, 0x80, v144
	v_ashrrev_i32_e32 v91, 31, v90
	v_lshlrev_b64 v[102:103], 12, v[90:91]
	s_waitcnt lgkmcnt(0)
	v_lshl_add_u64 v[64:65], v[142:143], 0, v[102:103]
	v_lshl_add_u64 v[252:253], v[64:65], 0, v[242:243]
	global_load_dwordx4 v[208:211], v[252:253], off
	v_lshl_add_u64 v[252:253], v[64:65], 0, v[242:243]
	global_load_dwordx4 v[212:215], v[252:253], off offset:256
	v_add_u32_e32 v80, 0x90, v144
	v_add_u32_e32 v68, 0xa0, v144
	v_add_u32_e32 v64, 0xb0, v144
	v_ashrrev_i32_e32 v81, 31, v80
	v_ashrrev_i32_e32 v69, 31, v68
	v_ashrrev_i32_e32 v65, 31, v64
	v_lshlrev_b64 v[92:93], 12, v[80:81]
	v_lshlrev_b64 v[78:79], 12, v[68:69]
	v_lshlrev_b64 v[66:67], 12, v[64:65]
	v_lshl_add_u64 v[70:71], v[142:143], 0, v[92:93]
	v_lshl_add_u64 v[72:73], v[142:143], 0, v[78:79]
	v_lshl_add_u64 v[112:113], v[142:143], 0, v[66:67]
	v_lshl_add_u64 v[252:253], v[70:71], 0, v[242:243]
	global_load_dwordx4 v[216:219], v[252:253], off
	v_lshl_add_u64 v[252:253], v[70:71], 0, v[242:243]
	global_load_dwordx4 v[220:223], v[252:253], off offset:256
	v_lshl_add_u64 v[252:253], v[72:73], 0, v[242:243]
	global_load_dwordx4 v[224:227], v[252:253], off
	v_lshl_add_u64 v[252:253], v[72:73], 0, v[242:243]
	global_load_dwordx4 v[228:231], v[252:253], off offset:256
	v_lshl_add_u64 v[252:253], v[112:113], 0, v[242:243]
	global_load_dwordx4 v[244:247], v[252:253], off
	s_nop 0
	v_lshl_add_u64 v[252:253], v[112:113], 0, v[242:243]
	global_load_dwordx4 v[248:251], v[252:253], off offset:256
	v_lshl_add_u64 v[102:103], s[34:35], 0, v[102:103]
	v_lshl_add_u64 v[102:103], v[140:141], 1, v[102:103]
	s_waitcnt vmcnt(7)
	v_permlane16_swap_b32 v208, v210
	v_permlane16_swap_b32 v209, v211
	v_lshlrev_b32_e32 v112, 16, v208
	v_and_b32_e32 v113, 0xffff0000, v208
	v_lshlrev_b32_e32 v104, 16, v209
	v_and_b32_e32 v105, 0xffff0000, v209
	s_waitcnt vmcnt(7)
	v_lshlrev_b32_e32 v114, 16, v210
	v_and_b32_e32 v115, 0xffff0000, v210
	v_lshlrev_b32_e32 v106, 16, v211
	v_and_b32_e32 v107, 0xffff0000, v211
	s_waitcnt vmcnt(6)
	v_permlane16_swap_b32 v212, v214
	v_permlane16_swap_b32 v213, v215
	v_lshlrev_b32_e32 v116, 16, v212
	v_and_b32_e32 v117, 0xffff0000, v212
	v_lshlrev_b32_e32 v108, 16, v213
	v_and_b32_e32 v109, 0xffff0000, v213
	s_waitcnt vmcnt(6)
	v_lshlrev_b32_e32 v118, 16, v214
	v_and_b32_e32 v119, 0xffff0000, v214
	v_pk_add_f32 v[62:63], v[62:63], v[104:105]
	v_pk_add_f32 v[60:61], v[60:61], v[112:113]
	v_pk_add_f32 v[58:59], v[58:59], v[106:107]
	v_pk_add_f32 v[56:57], v[56:57], v[114:115]
	v_lshlrev_b32_e32 v110, 16, v215
	v_and_b32_e32 v111, 0xffff0000, v215
	v_pk_add_f32 v[54:55], v[54:55], v[108:109]
	v_pk_add_f32 v[52:53], v[52:53], v[116:117]
	v_pk_add_f32 v[104:105], v[48:49], v[118:119]
	v_mul_f32_e32 v106, v61, v61
	v_mul_f32_e32 v107, v63, v63
	v_cvt_pk_bf16_f32 v232, v60, v61
	v_cvt_pk_bf16_f32 v233, v62, v63
	v_mul_f32_e32 v61, v57, v57
	v_mul_f32_e32 v63, v59, v59
	v_pk_add_f32 v[50:51], v[50:51], v[110:111]
	v_mul_f32_e32 v108, v53, v53
	v_mul_f32_e32 v109, v55, v55
	v_fmac_f32_e32 v106, v60, v60
	v_fmac_f32_e32 v107, v62, v62
	v_fmac_f32_e32 v61, v56, v56
	v_fmac_f32_e32 v63, v58, v58
	v_mul_f32_e32 v110, v105, v105
	v_mul_f32_e32 v111, v51, v51
	v_cvt_pk_bf16_f32 v234, v56, v57
	v_fmac_f32_e32 v108, v52, v52
	v_fmac_f32_e32 v109, v54, v54
	v_add_f32_e32 v49, v106, v107
	v_add_f32_e32 v56, v61, v63
	v_fmac_f32_e32 v110, v104, v104
	v_fmac_f32_e32 v111, v50, v50
	v_add_f32_e32 v57, v108, v109
	v_add_f32_e32 v49, v49, v56
	v_add_f32_e32 v49, v49, v57
	v_add_f32_e32 v56, v110, v111
	v_add_f32_e32 v56, v49, v56
	ds_bpermute_b32 v57, v184, v56
	v_cvt_pk_bf16_f32 v235, v58, v59
	s_nop 1
	v_permlane16_swap_b32 v232, v234
	v_permlane16_swap_b32 v233, v235
	v_lshl_add_u64 v[240:241], v[102:103], 0, v[242:243]
	global_store_dwordx4 v[240:241], v[232:235], off
	v_cvt_pk_bf16_f32 v236, v52, v53
	v_cvt_pk_bf16_f32 v237, v54, v55
	s_waitcnt lgkmcnt(0)
	v_add_f32_e32 v48, v56, v57
	ds_bpermute_b32 v49, v185, v48
	v_cvt_pk_bf16_f32 v238, v104, v105
	v_cvt_pk_bf16_f32 v239, v50, v51
	s_nop 1
	v_permlane16_swap_b32 v236, v238
	v_permlane16_swap_b32 v237, v239
	v_lshl_add_u64 v[240:241], v[102:103], 0, v[242:243]
	global_store_dwordx4 v[240:241], v[236:239], off offset:256
	s_and_saveexec_b64 s[40:41], s[8:9]
	s_cbranch_execz .LBB0_763
	v_lshl_add_u64 v[50:51], v[90:91], 2, s[12:13]
	s_waitcnt lgkmcnt(0)
	v_add_f32_e32 v48, v48, v49
	global_atomic_add_f32 v[50:51], v48, off
.LBB0_763:
	s_or_b64 exec, exec, s[40:41]
	s_waitcnt vmcnt(7)
	v_permlane16_swap_b32 v216, v218
	v_permlane16_swap_b32 v217, v219
	v_lshlrev_b32_e32 v48, 16, v216
	s_waitcnt lgkmcnt(0)
	v_and_b32_e32 v49, 0xffff0000, v216
	v_lshlrev_b32_e32 v50, 16, v217
	v_and_b32_e32 v51, 0xffff0000, v217
	v_pk_add_f32 v[46:47], v[46:47], v[50:51]
	v_pk_add_f32 v[44:45], v[44:45], v[48:49]
	v_mul_f32_e32 v49, v47, v47
	v_mul_f32_e32 v48, v45, v45
	s_waitcnt vmcnt(7)
	v_lshlrev_b32_e32 v52, 16, v218
	v_and_b32_e32 v53, 0xffff0000, v218
	v_lshlrev_b32_e32 v54, 16, v219
	v_and_b32_e32 v55, 0xffff0000, v219
	v_fmac_f32_e32 v48, v44, v44
	v_fmac_f32_e32 v49, v46, v46
	v_cvt_pk_bf16_f32 v232, v44, v45
	v_cvt_pk_bf16_f32 v233, v46, v47
	v_lshl_add_u64 v[46:47], s[34:35], 0, v[92:93]
	v_lshl_add_u64 v[46:47], v[140:141], 1, v[46:47]
	v_pk_add_f32 v[42:43], v[42:43], v[54:55]
	v_pk_add_f32 v[40:41], v[40:41], v[52:53]
	s_waitcnt vmcnt(6)
	v_permlane16_swap_b32 v220, v222
	v_permlane16_swap_b32 v221, v223
	v_lshlrev_b32_e32 v56, 16, v220
	v_and_b32_e32 v57, 0xffff0000, v220
	v_lshlrev_b32_e32 v58, 16, v221
	v_and_b32_e32 v59, 0xffff0000, v221
	v_mul_f32_e32 v44, v41, v41
	v_mul_f32_e32 v45, v43, v43
	v_fmac_f32_e32 v44, v40, v40
	v_fmac_f32_e32 v45, v42, v42
	v_pk_add_f32 v[38:39], v[38:39], v[58:59]
	v_pk_add_f32 v[36:37], v[36:37], v[56:57]
	v_add_f32_e32 v44, v44, v45
	v_cvt_pk_bf16_f32 v234, v40, v41
	v_mul_f32_e32 v41, v37, v37
	v_mul_f32_e32 v45, v39, v39
	v_add_f32_e32 v48, v48, v49
	v_fmac_f32_e32 v41, v36, v36
	v_fmac_f32_e32 v45, v38, v38
	s_waitcnt vmcnt(6)
	v_lshlrev_b32_e32 v60, 16, v222
	v_and_b32_e32 v61, 0xffff0000, v222
	v_lshlrev_b32_e32 v62, 16, v223
	v_and_b32_e32 v63, 0xffff0000, v223
	v_add_f32_e32 v44, v48, v44
	v_add_f32_e32 v41, v41, v45
	v_add_f32_e32 v41, v44, v41
	v_pk_add_f32 v[34:35], v[34:35], v[62:63]
	v_pk_add_f32 v[44:45], v[32:33], v[60:61]
	v_mul_f32_e32 v33, v35, v35
	v_mul_f32_e32 v32, v45, v45
	v_fmac_f32_e32 v32, v44, v44
	v_fmac_f32_e32 v33, v34, v34
	v_add_f32_e32 v32, v32, v33
	v_add_f32_e32 v32, v41, v32
	ds_bpermute_b32 v33, v184, v32
	v_cvt_pk_bf16_f32 v235, v42, v43
	s_nop 1
	v_permlane16_swap_b32 v232, v234
	v_permlane16_swap_b32 v233, v235
	v_lshl_add_u64 v[240:241], v[46:47], 0, v[242:243]
	global_store_dwordx4 v[240:241], v[232:235], off
	v_cvt_pk_bf16_f32 v236, v36, v37
	v_cvt_pk_bf16_f32 v237, v38, v39
	s_waitcnt lgkmcnt(0)
	v_add_f32_e32 v32, v32, v33
	ds_bpermute_b32 v33, v185, v32
	v_cvt_pk_bf16_f32 v238, v44, v45
	v_cvt_pk_bf16_f32 v239, v34, v35
	s_nop 1
	v_permlane16_swap_b32 v236, v238
	v_permlane16_swap_b32 v237, v239
	v_lshl_add_u64 v[240:241], v[46:47], 0, v[242:243]
	global_store_dwordx4 v[240:241], v[236:239], off offset:256
	s_and_saveexec_b64 s[40:41], s[8:9]
	s_cbranch_execz .LBB0_765
	v_lshl_add_u64 v[34:35], v[80:81], 2, s[12:13]
	s_waitcnt lgkmcnt(0)
	v_add_f32_e32 v32, v32, v33
	global_atomic_add_f32 v[34:35], v32, off
.LBB0_765:
	s_or_b64 exec, exec, s[40:41]
	s_waitcnt vmcnt(7)
	v_permlane16_swap_b32 v224, v226
	v_permlane16_swap_b32 v225, v227
	v_lshlrev_b32_e32 v32, 16, v224
	s_waitcnt lgkmcnt(0)
	v_and_b32_e32 v33, 0xffff0000, v224
	v_lshlrev_b32_e32 v34, 16, v225
	v_and_b32_e32 v35, 0xffff0000, v225
	v_pk_add_f32 v[30:31], v[30:31], v[34:35]
	v_pk_add_f32 v[28:29], v[28:29], v[32:33]
	v_mul_f32_e32 v33, v31, v31
	v_mul_f32_e32 v32, v29, v29
	s_waitcnt vmcnt(7)
	v_lshlrev_b32_e32 v36, 16, v226
	v_and_b32_e32 v37, 0xffff0000, v226
	v_lshlrev_b32_e32 v38, 16, v227
	v_and_b32_e32 v39, 0xffff0000, v227
	v_fmac_f32_e32 v32, v28, v28
	v_fmac_f32_e32 v33, v30, v30
	v_cvt_pk_bf16_f32 v232, v28, v29
	v_cvt_pk_bf16_f32 v233, v30, v31
	v_lshl_add_u64 v[30:31], s[34:35], 0, v[78:79]
	v_lshl_add_u64 v[30:31], v[140:141], 1, v[30:31]
	v_pk_add_f32 v[26:27], v[26:27], v[38:39]
	v_pk_add_f32 v[24:25], v[24:25], v[36:37]
	s_waitcnt vmcnt(6)
	v_permlane16_swap_b32 v228, v230
	v_permlane16_swap_b32 v229, v231
	v_lshlrev_b32_e32 v40, 16, v228
	v_and_b32_e32 v41, 0xffff0000, v228
	v_lshlrev_b32_e32 v42, 16, v229
	v_and_b32_e32 v43, 0xffff0000, v229
	v_mul_f32_e32 v28, v25, v25
	v_mul_f32_e32 v29, v27, v27
	v_fmac_f32_e32 v28, v24, v24
	v_fmac_f32_e32 v29, v26, v26
	v_pk_add_f32 v[22:23], v[22:23], v[42:43]
	v_pk_add_f32 v[20:21], v[20:21], v[40:41]
	v_add_f32_e32 v28, v28, v29
	v_cvt_pk_bf16_f32 v234, v24, v25
	v_mul_f32_e32 v25, v21, v21
	v_mul_f32_e32 v29, v23, v23
	v_add_f32_e32 v32, v32, v33
	v_fmac_f32_e32 v25, v20, v20
	v_fmac_f32_e32 v29, v22, v22
	s_waitcnt vmcnt(6)
	v_lshlrev_b32_e32 v44, 16, v230
	v_and_b32_e32 v45, 0xffff0000, v230
	v_lshlrev_b32_e32 v46, 16, v231
	v_and_b32_e32 v47, 0xffff0000, v231
	v_add_f32_e32 v28, v32, v28
	v_add_f32_e32 v25, v25, v29
	v_add_f32_e32 v25, v28, v25
	v_pk_add_f32 v[18:19], v[18:19], v[46:47]
	v_pk_add_f32 v[28:29], v[16:17], v[44:45]
	v_mul_f32_e32 v17, v19, v19
	v_mul_f32_e32 v16, v29, v29
	v_fmac_f32_e32 v16, v28, v28
	v_fmac_f32_e32 v17, v18, v18
	v_add_f32_e32 v16, v16, v17
	v_add_f32_e32 v16, v25, v16
	ds_bpermute_b32 v17, v184, v16
	v_cvt_pk_bf16_f32 v235, v26, v27
	s_nop 1
	v_permlane16_swap_b32 v232, v234
	v_permlane16_swap_b32 v233, v235
	v_lshl_add_u64 v[240:241], v[30:31], 0, v[242:243]
	global_store_dwordx4 v[240:241], v[232:235], off
	v_cvt_pk_bf16_f32 v236, v20, v21
	v_cvt_pk_bf16_f32 v237, v22, v23
	s_waitcnt lgkmcnt(0)
	v_add_f32_e32 v16, v16, v17
	ds_bpermute_b32 v17, v185, v16
	v_cvt_pk_bf16_f32 v238, v28, v29
	v_cvt_pk_bf16_f32 v239, v18, v19
	s_nop 1
	v_permlane16_swap_b32 v236, v238
	v_permlane16_swap_b32 v237, v239
	v_lshl_add_u64 v[240:241], v[30:31], 0, v[242:243]
	global_store_dwordx4 v[240:241], v[236:239], off offset:256
	s_and_saveexec_b64 s[40:41], s[8:9]
	s_cbranch_execz .LBB0_767
	v_lshl_add_u64 v[18:19], v[68:69], 2, s[12:13]
	s_waitcnt lgkmcnt(0)
	v_add_f32_e32 v16, v16, v17
	global_atomic_add_f32 v[18:19], v16, off
.LBB0_767:
	s_or_b64 exec, exec, s[40:41]
	s_waitcnt vmcnt(7)
	v_permlane16_swap_b32 v244, v246
	v_permlane16_swap_b32 v245, v247
	v_lshlrev_b32_e32 v16, 16, v244
	s_waitcnt lgkmcnt(0)
	v_and_b32_e32 v17, 0xffff0000, v244
	v_lshlrev_b32_e32 v18, 16, v245
	v_and_b32_e32 v19, 0xffff0000, v245
	v_pk_add_f32 v[14:15], v[14:15], v[18:19]
	v_pk_add_f32 v[12:13], v[12:13], v[16:17]
	v_mul_f32_e32 v17, v15, v15
	v_mul_f32_e32 v16, v13, v13
	s_waitcnt vmcnt(7)
	v_lshlrev_b32_e32 v20, 16, v246
	v_and_b32_e32 v21, 0xffff0000, v246
	v_lshlrev_b32_e32 v22, 16, v247
	v_and_b32_e32 v23, 0xffff0000, v247
	v_fmac_f32_e32 v16, v12, v12
	v_fmac_f32_e32 v17, v14, v14
	v_cvt_pk_bf16_f32 v232, v12, v13
	v_cvt_pk_bf16_f32 v233, v14, v15
	v_lshl_add_u64 v[14:15], s[34:35], 0, v[66:67]
	v_lshl_add_u64 v[14:15], v[140:141], 1, v[14:15]
	v_pk_add_f32 v[10:11], v[10:11], v[22:23]
	v_pk_add_f32 v[8:9], v[8:9], v[20:21]
	s_waitcnt vmcnt(6)
	v_permlane16_swap_b32 v248, v250
	v_permlane16_swap_b32 v249, v251
	v_lshlrev_b32_e32 v24, 16, v248
	v_and_b32_e32 v25, 0xffff0000, v248
	v_lshlrev_b32_e32 v26, 16, v249
	v_and_b32_e32 v27, 0xffff0000, v249
	v_mul_f32_e32 v12, v9, v9
	v_mul_f32_e32 v13, v11, v11
	v_fmac_f32_e32 v12, v8, v8
	v_fmac_f32_e32 v13, v10, v10
	v_pk_add_f32 v[6:7], v[6:7], v[26:27]
	v_pk_add_f32 v[4:5], v[4:5], v[24:25]
	v_add_f32_e32 v12, v12, v13
	v_cvt_pk_bf16_f32 v234, v8, v9
	v_mul_f32_e32 v9, v5, v5
	v_mul_f32_e32 v13, v7, v7
	v_add_f32_e32 v16, v16, v17
	v_fmac_f32_e32 v9, v4, v4
	v_fmac_f32_e32 v13, v6, v6
	s_waitcnt vmcnt(6)
	v_lshlrev_b32_e32 v28, 16, v250
	v_and_b32_e32 v29, 0xffff0000, v250
	v_lshlrev_b32_e32 v30, 16, v251
	v_and_b32_e32 v31, 0xffff0000, v251
	v_add_f32_e32 v12, v16, v12
	v_add_f32_e32 v9, v9, v13
	v_add_f32_e32 v9, v12, v9
	v_pk_add_f32 v[2:3], v[2:3], v[30:31]
	v_pk_add_f32 v[12:13], v[0:1], v[28:29]
	v_mul_f32_e32 v1, v3, v3
	v_mul_f32_e32 v0, v13, v13
	v_fmac_f32_e32 v0, v12, v12
	v_fmac_f32_e32 v1, v2, v2
	v_add_f32_e32 v0, v0, v1
	v_add_f32_e32 v0, v9, v0
	ds_bpermute_b32 v1, v184, v0
	v_cvt_pk_bf16_f32 v235, v10, v11
	s_nop 1
	v_permlane16_swap_b32 v232, v234
	v_permlane16_swap_b32 v233, v235
	v_lshl_add_u64 v[240:241], v[14:15], 0, v[242:243]
	global_store_dwordx4 v[240:241], v[232:235], off
	v_cvt_pk_bf16_f32 v236, v4, v5
	v_cvt_pk_bf16_f32 v237, v6, v7
	s_waitcnt lgkmcnt(0)
	v_add_f32_e32 v0, v0, v1
	ds_bpermute_b32 v1, v185, v0
	v_cvt_pk_bf16_f32 v238, v12, v13
	v_cvt_pk_bf16_f32 v239, v2, v3
	s_nop 1
	v_permlane16_swap_b32 v236, v238
	v_permlane16_swap_b32 v237, v239
	v_lshl_add_u64 v[240:241], v[14:15], 0, v[242:243]
	global_store_dwordx4 v[240:241], v[236:239], off offset:256
	s_and_saveexec_b64 s[40:41], s[8:9]
	s_cbranch_execz .LBB0_769
	v_lshl_add_u64 v[2:3], v[64:65], 2, s[12:13]
	s_waitcnt lgkmcnt(0)
	v_add_f32_e32 v0, v0, v1
	global_atomic_add_f32 v[2:3], v0, off

.LBB0_929:
	v_mbcnt_lo_u32_b32 v148, -1, 0
	v_mbcnt_hi_u32_b32 v148, -1, v148
	v_bfe_u32 v148, v148, 4, 1
	v_mul_u32_u24_e32 v148, 24, v148
	v_mov_b32_e32 v149, 0
	v_lshl_add_u32 v142, s39, 8, v144
	v_lshl_or_b32 v154, s40, 8, v146
	v_ashrrev_i32_e32 v155, 31, v154
	v_ashrrev_i32_e32 v143, 31, v142
	v_lshl_add_u64 v[140:141], v[154:155], 1, s[34:35]
	v_lshlrev_b64 v[150:151], 12, v[142:143]
	v_lshl_add_u64 v[150:151], v[140:141], 0, v[150:151]
	v_or_b32_e32 v160, 16, v142
	v_lshl_add_u64 v[226:227], v[150:151], 0, v[148:149]
	global_load_dwordx4 v[226:229], v[226:227], off
	v_lshl_add_u64 v[230:231], v[150:151], 0, v[148:149]
	global_load_dwordx4 v[230:233], v[230:231], off offset:256
	v_ashrrev_i32_e32 v161, 31, v160
	v_lshlrev_b64 v[162:163], 12, v[160:161]
	v_lshl_add_u64 v[162:163], v[140:141], 0, v[162:163]
	v_or_b32_e32 v170, 32, v142
	v_lshl_add_u64 v[234:235], v[162:163], 0, v[148:149]
	global_load_dwordx4 v[234:237], v[234:235], off
	v_lshl_add_u64 v[238:239], v[162:163], 0, v[148:149]
	global_load_dwordx4 v[238:241], v[238:239], off offset:256
	v_ashrrev_i32_e32 v171, 31, v170
	v_lshlrev_b64 v[172:173], 12, v[170:171]
	v_lshl_add_u64 v[172:173], v[140:141], 0, v[172:173]
	v_or_b32_e32 v180, 48, v142
	v_lshl_add_u64 v[242:243], v[172:173], 0, v[148:149]
	global_load_dwordx4 v[242:245], v[242:243], off
	v_lshl_add_u64 v[246:247], v[172:173], 0, v[148:149]
	global_load_dwordx4 v[246:249], v[246:247], off offset:256
	v_ashrrev_i32_e32 v181, 31, v180
	v_lshlrev_b64 v[182:183], 12, v[180:181]
	v_lshl_add_u64 v[182:183], v[140:141], 0, v[182:183]
	v_lshl_add_u64 v[250:251], v[182:183], 0, v[148:149]
	global_load_dwordx4 v[250:253], v[250:251], off
	global_load_dwordx2 v[188:189], v[182:183], off offset:256
	s_nop 0
	global_load_dwordx2 v[182:183], v[182:183], off offset:288
	v_lshlrev_b64 v[224:225], 13, v[142:143]
	s_and_b64 vcc, exec, s[0:1]
	s_mov_b64 s[0:1], -1
	s_waitcnt vmcnt(0)
	v_permlane16_swap_b32 v226, v228
	v_permlane16_swap_b32 v227, v229
	v_lshlrev_b32_e32 v190, 16, v226
	v_and_b32_e32 v191, 0xffff0000, v226
	v_lshlrev_b32_e32 v152, 16, v227
	v_and_b32_e32 v153, 0xffff0000, v227
	v_permlane16_swap_b32 v230, v232
	v_permlane16_swap_b32 v231, v233
	v_lshlrev_b32_e32 v194, 16, v230
	v_and_b32_e32 v195, 0xffff0000, v230
	v_lshlrev_b32_e32 v158, 16, v231
	v_and_b32_e32 v159, 0xffff0000, v231
	v_lshlrev_b32_e32 v196, 16, v232
	v_and_b32_e32 v197, 0xffff0000, v232
	v_lshlrev_b32_e32 v198, 16, v233
	v_and_b32_e32 v199, 0xffff0000, v233
	v_pk_fma_f32 v[152:153], v[126:127], 0.5, v[152:153] op_sel_hi:[1,0,1]
	v_pk_fma_f32 v[150:151], v[124:125], 0.5, v[190:191] op_sel_hi:[1,0,1]
	v_lshl_add_u64 v[126:127], s[30:31], 0, v[224:225]
	v_lshlrev_b64 v[124:125], 2, v[154:155]
	v_lshl_add_u64 v[126:127], v[126:127], 0, v[124:125]
	v_pk_fma_f32 v[118:119], v[118:119], 0.5, v[158:159] op_sel_hi:[1,0,1]
	v_pk_fma_f32 v[116:117], v[116:117], 0.5, v[194:195] op_sel_hi:[1,0,1]
	v_permlane16_swap_b32 v234, v236
	v_permlane16_swap_b32 v235, v237
	v_lshlrev_b32_e32 v200, 16, v234
	v_and_b32_e32 v201, 0xffff0000, v234
	global_store_dwordx4 v[126:127], v[116:119], off offset:512 nt
	v_pk_fma_f32 v[110:111], v[110:111], 0.5, v[198:199] op_sel_hi:[1,0,1]
	v_pk_fma_f32 v[108:109], v[108:109], 0.5, v[196:197] op_sel_hi:[1,0,1]
	v_lshlrev_b64 v[116:117], 13, v[160:161]
	v_permlane16_swap_b32 v238, v240
	v_permlane16_swap_b32 v239, v241
	v_lshlrev_b32_e32 v204, 16, v238
	v_and_b32_e32 v205, 0xffff0000, v238
	v_lshlrev_b32_e32 v168, 16, v239
	v_and_b32_e32 v169, 0xffff0000, v239
	global_store_dwordx4 v[126:127], v[108:111], off offset:576 nt
	v_lshlrev_b32_e32 v206, 16, v240
	v_and_b32_e32 v207, 0xffff0000, v240
	v_pk_fma_f32 v[108:109], v[112:113], 0.5, v[200:201] op_sel_hi:[1,0,1]
	v_lshl_add_u64 v[112:113], s[30:31], 0, v[116:117]
	v_lshlrev_b32_e32 v162, 16, v241
	v_and_b32_e32 v163, 0xffff0000, v241
	v_lshl_add_u64 v[112:113], v[112:113], 0, v[124:125]
	v_pk_fma_f32 v[102:103], v[102:103], 0.5, v[168:169] op_sel_hi:[1,0,1]
	v_pk_fma_f32 v[100:101], v[100:101], 0.5, v[204:205] op_sel_hi:[1,0,1]
	v_permlane16_swap_b32 v242, v244
	v_permlane16_swap_b32 v243, v245
	v_lshlrev_b32_e32 v208, 16, v242
	v_and_b32_e32 v209, 0xffff0000, v242
	global_store_dwordx4 v[112:113], v[100:103], off offset:512 nt
	v_pk_fma_f32 v[94:95], v[94:95], 0.5, v[162:163] op_sel_hi:[1,0,1]
	v_pk_fma_f32 v[92:93], v[92:93], 0.5, v[206:207] op_sel_hi:[1,0,1]
	v_lshlrev_b64 v[100:101], 13, v[170:171]
	v_permlane16_swap_b32 v246, v248
	v_permlane16_swap_b32 v247, v249
	v_lshlrev_b32_e32 v212, 16, v246
	v_and_b32_e32 v213, 0xffff0000, v246
	v_lshlrev_b32_e32 v178, 16, v247
	v_and_b32_e32 v179, 0xffff0000, v247
	global_store_dwordx4 v[112:113], v[92:95], off offset:576 nt
	v_lshlrev_b32_e32 v214, 16, v248
	v_and_b32_e32 v215, 0xffff0000, v248
	v_pk_fma_f32 v[92:93], v[96:97], 0.5, v[208:209] op_sel_hi:[1,0,1]
	v_lshl_add_u64 v[96:97], s[30:31], 0, v[100:101]
	v_lshlrev_b32_e32 v172, 16, v249
	v_and_b32_e32 v173, 0xffff0000, v249
	v_lshl_add_u64 v[96:97], v[96:97], 0, v[124:125]
	v_pk_fma_f32 v[86:87], v[86:87], 0.5, v[178:179] op_sel_hi:[1,0,1]
	v_pk_fma_f32 v[84:85], v[84:85], 0.5, v[212:213] op_sel_hi:[1,0,1]
	v_permlane16_swap_b32 v250, v252
	v_permlane16_swap_b32 v251, v253
	v_lshlrev_b32_e32 v216, 16, v250
	v_and_b32_e32 v217, 0xffff0000, v250
	global_store_dwordx4 v[96:97], v[84:87], off offset:512 nt
	v_pk_fma_f32 v[78:79], v[78:79], 0.5, v[172:173] op_sel_hi:[1,0,1]
	v_pk_fma_f32 v[76:77], v[76:77], 0.5, v[214:215] op_sel_hi:[1,0,1]
	v_lshlrev_b64 v[84:85], 13, v[180:181]
	v_lshlrev_b32_e32 v222, 16, v182
	v_and_b32_e32 v223, 0xffff0000, v182
	v_lshlrev_b32_e32 v182, 16, v183
	v_and_b32_e32 v183, 0xffff0000, v183
	global_store_dwordx4 v[96:97], v[76:79], off offset:576 nt
	v_pk_fma_f32 v[66:67], v[66:67], 0.5, v[182:183] op_sel_hi:[1,0,1]
	v_pk_fma_f32 v[64:65], v[64:65], 0.5, v[222:223] op_sel_hi:[1,0,1]
	v_pk_fma_f32 v[76:77], v[80:81], 0.5, v[216:217] op_sel_hi:[1,0,1]
	v_lshl_add_u64 v[80:81], s[30:31], 0, v[84:85]
	v_lshl_add_u64 v[80:81], v[80:81], 0, v[124:125]
	v_lshlrev_b32_e32 v192, 16, v228
	v_and_b32_e32 v193, 0xffff0000, v228
	v_lshlrev_b32_e32 v156, 16, v229
	v_and_b32_e32 v157, 0xffff0000, v229
	v_lshlrev_b32_e32 v164, 16, v235
	v_and_b32_e32 v165, 0xffff0000, v235
	v_lshlrev_b32_e32 v202, 16, v236
	v_and_b32_e32 v203, 0xffff0000, v236
	v_lshlrev_b32_e32 v166, 16, v237
	v_and_b32_e32 v167, 0xffff0000, v237
	v_lshlrev_b32_e32 v174, 16, v243
	v_and_b32_e32 v175, 0xffff0000, v243
	v_lshlrev_b32_e32 v210, 16, v244
	v_and_b32_e32 v211, 0xffff0000, v244
	v_lshlrev_b32_e32 v176, 16, v245
	v_and_b32_e32 v177, 0xffff0000, v245
	v_lshlrev_b32_e32 v184, 16, v251
	v_and_b32_e32 v185, 0xffff0000, v251
	v_lshlrev_b32_e32 v218, 16, v252
	v_and_b32_e32 v219, 0xffff0000, v252
	v_lshlrev_b32_e32 v186, 16, v253
	v_and_b32_e32 v187, 0xffff0000, v253
	v_lshlrev_b32_e32 v220, 16, v188
	v_and_b32_e32 v221, 0xffff0000, v188
	v_lshlrev_b32_e32 v188, 16, v189
	v_and_b32_e32 v189, 0xffff0000, v189
	global_store_dwordx4 v[80:81], v[64:67], off offset:576 nt
	v_pk_fma_f32 v[122:123], v[122:123], 0.5, v[156:157] op_sel_hi:[1,0,1]
	v_pk_fma_f32 v[120:121], v[120:121], 0.5, v[192:193] op_sel_hi:[1,0,1]
	v_add_u32_e32 v64, 0x80, v142
	v_pk_fma_f32 v[110:111], v[114:115], 0.5, v[164:165] op_sel_hi:[1,0,1]
	v_pk_fma_f32 v[106:107], v[106:107], 0.5, v[166:167] op_sel_hi:[1,0,1]
	v_pk_fma_f32 v[104:105], v[104:105], 0.5, v[202:203] op_sel_hi:[1,0,1]
	v_pk_fma_f32 v[94:95], v[98:99], 0.5, v[174:175] op_sel_hi:[1,0,1]
	v_pk_fma_f32 v[90:91], v[90:91], 0.5, v[176:177] op_sel_hi:[1,0,1]
	v_pk_fma_f32 v[88:89], v[88:89], 0.5, v[210:211] op_sel_hi:[1,0,1]
	v_pk_fma_f32 v[78:79], v[82:83], 0.5, v[184:185] op_sel_hi:[1,0,1]
	v_pk_fma_f32 v[74:75], v[74:75], 0.5, v[186:187] op_sel_hi:[1,0,1]
	v_pk_fma_f32 v[72:73], v[72:73], 0.5, v[218:219] op_sel_hi:[1,0,1]
	v_pk_fma_f32 v[70:71], v[70:71], 0.5, v[188:189] op_sel_hi:[1,0,1]
	v_pk_fma_f32 v[68:69], v[68:69], 0.5, v[220:221] op_sel_hi:[1,0,1]
	v_ashrrev_i32_e32 v65, 31, v64
	global_store_dwordx4 v[126:127], v[150:153], off nt
	global_store_dwordx4 v[126:127], v[120:123], off offset:64 nt
	global_store_dwordx4 v[112:113], v[108:111], off nt
	global_store_dwordx4 v[112:113], v[104:107], off offset:64 nt
	global_store_dwordx4 v[96:97], v[92:95], off nt
	global_store_dwordx4 v[96:97], v[88:91], off offset:64 nt
	global_store_dwordx4 v[80:81], v[76:79], off nt
	global_store_dwordx4 v[80:81], v[72:75], off offset:64 nt
	global_store_dwordx4 v[80:81], v[68:71], off offset:512 nt
	v_lshlrev_b64 v[66:67], 12, v[64:65]
	v_lshl_add_u64 v[66:67], v[140:141], 0, v[66:67]
	v_lshl_add_u64 v[226:227], v[66:67], 0, v[148:149]
	global_load_dwordx4 v[226:229], v[226:227], off
	v_lshl_add_u64 v[230:231], v[66:67], 0, v[148:149]
	global_load_dwordx4 v[230:233], v[230:231], off offset:256
	v_add_u32_e32 v66, 0x90, v142
	v_ashrrev_i32_e32 v67, 31, v66
	v_lshlrev_b64 v[76:77], 12, v[66:67]
	v_lshl_add_u64 v[76:77], v[140:141], 0, v[76:77]
	v_lshl_add_u64 v[234:235], v[76:77], 0, v[148:149]
	global_load_dwordx4 v[234:237], v[234:235], off
	v_lshl_add_u64 v[238:239], v[76:77], 0, v[148:149]
	global_load_dwordx4 v[238:241], v[238:239], off offset:256
	v_add_u32_e32 v76, 0xa0, v142
	v_ashrrev_i32_e32 v77, 31, v76
	v_lshlrev_b64 v[86:87], 12, v[76:77]
	v_lshl_add_u64 v[86:87], v[140:141], 0, v[86:87]
	v_lshl_add_u64 v[242:243], v[86:87], 0, v[148:149]
	global_load_dwordx4 v[242:245], v[242:243], off
	v_lshl_add_u64 v[246:247], v[86:87], 0, v[148:149]
	global_load_dwordx4 v[246:249], v[246:247], off offset:256
	v_add_u32_e32 v86, 0xb0, v142
	v_ashrrev_i32_e32 v87, 31, v86
	v_lshlrev_b64 v[96:97], 12, v[86:87]
	v_lshl_add_u64 v[96:97], v[140:141], 0, v[96:97]
	v_lshl_add_u64 v[250:251], v[96:97], 0, v[148:149]
	global_load_dwordx4 v[250:253], v[250:251], off
	global_load_dwordx2 v[102:103], v[96:97], off offset:256
	global_load_dwordx2 v[104:105], v[96:97], off offset:288
	v_lshlrev_b64 v[64:65], 13, v[64:65]
	v_lshl_add_u64 v[64:65], s[30:31], 0, v[64:65]
	v_lshl_add_u64 v[64:65], v[64:65], 0, v[124:125]
	s_waitcnt vmcnt(8)
	v_permlane16_swap_b32 v226, v228
	v_permlane16_swap_b32 v227, v229
	v_lshlrev_b32_e32 v96, 16, v226
	v_and_b32_e32 v97, 0xffff0000, v226
	s_waitcnt vmcnt(7)
	v_permlane16_swap_b32 v230, v232
	v_permlane16_swap_b32 v231, v233
	v_lshlrev_b32_e32 v108, 16, v230
	v_and_b32_e32 v109, 0xffff0000, v230
	v_lshlrev_b32_e32 v72, 16, v231
	v_and_b32_e32 v73, 0xffff0000, v231
	s_waitcnt vmcnt(7)
	v_lshlrev_b32_e32 v110, 16, v232
	v_and_b32_e32 v111, 0xffff0000, v232
	v_lshlrev_b32_e32 v74, 16, v233
	v_and_b32_e32 v75, 0xffff0000, v233
	v_pk_fma_f32 v[54:55], v[54:55], 0.5, v[72:73] op_sel_hi:[1,0,1]
	v_pk_fma_f32 v[52:53], v[52:53], 0.5, v[108:109] op_sel_hi:[1,0,1]
	s_waitcnt vmcnt(6)
	v_permlane16_swap_b32 v234, v236
	v_permlane16_swap_b32 v235, v237
	v_lshlrev_b32_e32 v112, 16, v234
	v_and_b32_e32 v113, 0xffff0000, v234
	global_store_dwordx4 v[64:65], v[52:55], off offset:512 nt
	v_pk_fma_f32 v[46:47], v[46:47], 0.5, v[74:75] op_sel_hi:[1,0,1]
	v_pk_fma_f32 v[44:45], v[44:45], 0.5, v[110:111] op_sel_hi:[1,0,1]
	v_lshlrev_b64 v[52:53], 13, v[66:67]
	s_waitcnt vmcnt(6)
	v_permlane16_swap_b32 v238, v240
	v_permlane16_swap_b32 v239, v241
	v_lshlrev_b32_e32 v116, 16, v238
	v_and_b32_e32 v117, 0xffff0000, v238
	v_lshlrev_b32_e32 v82, 16, v239
	v_and_b32_e32 v83, 0xffff0000, v239
	global_store_dwordx4 v[64:65], v[44:47], off offset:576 nt
	s_waitcnt vmcnt(7)
	v_lshlrev_b32_e32 v118, 16, v240
	v_and_b32_e32 v119, 0xffff0000, v240
	v_pk_fma_f32 v[44:45], v[48:49], 0.5, v[112:113] op_sel_hi:[1,0,1]
	v_lshl_add_u64 v[48:49], s[30:31], 0, v[52:53]
	v_lshlrev_b32_e32 v84, 16, v241
	v_and_b32_e32 v85, 0xffff0000, v241
	v_lshl_add_u64 v[48:49], v[48:49], 0, v[124:125]
	v_pk_fma_f32 v[38:39], v[38:39], 0.5, v[82:83] op_sel_hi:[1,0,1]
	v_pk_fma_f32 v[36:37], v[36:37], 0.5, v[116:117] op_sel_hi:[1,0,1]
	s_waitcnt vmcnt(6)
	v_permlane16_swap_b32 v242, v244
	v_permlane16_swap_b32 v243, v245
	v_lshlrev_b32_e32 v120, 16, v242
	v_and_b32_e32 v121, 0xffff0000, v242
	global_store_dwordx4 v[48:49], v[36:39], off offset:512 nt
	v_pk_fma_f32 v[30:31], v[30:31], 0.5, v[84:85] op_sel_hi:[1,0,1]
	v_pk_fma_f32 v[28:29], v[28:29], 0.5, v[118:119] op_sel_hi:[1,0,1]
	v_lshlrev_b64 v[36:37], 13, v[76:77]
	s_waitcnt vmcnt(6)
	v_permlane16_swap_b32 v246, v248
	v_permlane16_swap_b32 v247, v249
	v_lshlrev_b32_e32 v126, 16, v246
	v_and_b32_e32 v127, 0xffff0000, v246
	v_lshlrev_b32_e32 v92, 16, v247
	v_and_b32_e32 v93, 0xffff0000, v247
	global_store_dwordx4 v[48:49], v[28:31], off offset:576 nt
	s_waitcnt vmcnt(7)
	v_lshlrev_b32_e32 v140, 16, v248
	v_and_b32_e32 v141, 0xffff0000, v248
	v_pk_fma_f32 v[28:29], v[32:33], 0.5, v[120:121] op_sel_hi:[1,0,1]
	v_lshl_add_u64 v[32:33], s[30:31], 0, v[36:37]
	v_lshlrev_b32_e32 v94, 16, v249
	v_and_b32_e32 v95, 0xffff0000, v249
	v_lshl_add_u64 v[32:33], v[32:33], 0, v[124:125]
	v_pk_fma_f32 v[22:23], v[22:23], 0.5, v[92:93] op_sel_hi:[1,0,1]
	v_pk_fma_f32 v[20:21], v[20:21], 0.5, v[126:127] op_sel_hi:[1,0,1]
	s_waitcnt vmcnt(6)
	v_permlane16_swap_b32 v250, v252
	v_permlane16_swap_b32 v251, v253
	v_lshlrev_b32_e32 v142, 16, v250
	v_and_b32_e32 v143, 0xffff0000, v250
	global_store_dwordx4 v[32:33], v[20:23], off offset:512 nt
	v_pk_fma_f32 v[14:15], v[14:15], 0.5, v[94:95] op_sel_hi:[1,0,1]
	v_pk_fma_f32 v[12:13], v[12:13], 0.5, v[140:141] op_sel_hi:[1,0,1]
	v_lshlrev_b64 v[20:21], 13, v[86:87]
	v_lshlrev_b32_e32 v68, 16, v227
	v_and_b32_e32 v69, 0xffff0000, v227
	v_lshlrev_b32_e32 v106, 16, v228
	v_and_b32_e32 v107, 0xffff0000, v228
	v_lshlrev_b32_e32 v70, 16, v229
	v_and_b32_e32 v71, 0xffff0000, v229
	v_lshlrev_b32_e32 v78, 16, v235
	v_and_b32_e32 v79, 0xffff0000, v235
	v_lshlrev_b32_e32 v114, 16, v236
	v_and_b32_e32 v115, 0xffff0000, v236
	v_lshlrev_b32_e32 v80, 16, v237
	v_and_b32_e32 v81, 0xffff0000, v237
	v_lshlrev_b32_e32 v88, 16, v243
	v_and_b32_e32 v89, 0xffff0000, v243
	v_lshlrev_b32_e32 v122, 16, v244
	v_and_b32_e32 v123, 0xffff0000, v244
	v_lshlrev_b32_e32 v90, 16, v245
	v_and_b32_e32 v91, 0xffff0000, v245
	v_lshlrev_b32_e32 v98, 16, v251
	v_and_b32_e32 v99, 0xffff0000, v251
	s_waitcnt vmcnt(7)
	v_lshlrev_b32_e32 v150, 16, v252
	v_and_b32_e32 v151, 0xffff0000, v252
	v_lshlrev_b32_e32 v100, 16, v253
	v_and_b32_e32 v101, 0xffff0000, v253
	s_waitcnt vmcnt(6)
	v_lshlrev_b32_e32 v152, 16, v102
	v_and_b32_e32 v153, 0xffff0000, v102
	v_lshlrev_b32_e32 v102, 16, v103
	v_and_b32_e32 v103, 0xffff0000, v103
	s_waitcnt vmcnt(5)
	v_lshlrev_b32_e32 v154, 16, v104
	v_and_b32_e32 v155, 0xffff0000, v104
	v_lshlrev_b32_e32 v104, 16, v105
	v_and_b32_e32 v105, 0xffff0000, v105
	global_store_dwordx4 v[32:33], v[12:15], off offset:576 nt
	v_pk_fma_f32 v[62:63], v[62:63], 0.5, v[68:69] op_sel_hi:[1,0,1]
	v_pk_fma_f32 v[60:61], v[60:61], 0.5, v[96:97] op_sel_hi:[1,0,1]
	v_pk_fma_f32 v[12:13], v[16:17], 0.5, v[142:143] op_sel_hi:[1,0,1]
	v_lshl_add_u64 v[16:17], s[30:31], 0, v[20:21]
	v_pk_fma_f32 v[58:59], v[58:59], 0.5, v[70:71] op_sel_hi:[1,0,1]
	v_pk_fma_f32 v[56:57], v[56:57], 0.5, v[106:107] op_sel_hi:[1,0,1]
	v_pk_fma_f32 v[46:47], v[50:51], 0.5, v[78:79] op_sel_hi:[1,0,1]
	v_pk_fma_f32 v[42:43], v[42:43], 0.5, v[80:81] op_sel_hi:[1,0,1]
	v_pk_fma_f32 v[40:41], v[40:41], 0.5, v[114:115] op_sel_hi:[1,0,1]
	v_pk_fma_f32 v[30:31], v[34:35], 0.5, v[88:89] op_sel_hi:[1,0,1]
	v_pk_fma_f32 v[26:27], v[26:27], 0.5, v[90:91] op_sel_hi:[1,0,1]
	v_pk_fma_f32 v[24:25], v[24:25], 0.5, v[122:123] op_sel_hi:[1,0,1]
	v_pk_fma_f32 v[14:15], v[18:19], 0.5, v[98:99] op_sel_hi:[1,0,1]
	v_lshl_add_u64 v[16:17], v[16:17], 0, v[124:125]
	v_pk_fma_f32 v[10:11], v[10:11], 0.5, v[100:101] op_sel_hi:[1,0,1]
	v_pk_fma_f32 v[8:9], v[8:9], 0.5, v[150:151] op_sel_hi:[1,0,1]
	v_pk_fma_f32 v[6:7], v[6:7], 0.5, v[102:103] op_sel_hi:[1,0,1]
	v_pk_fma_f32 v[4:5], v[4:5], 0.5, v[152:153] op_sel_hi:[1,0,1]
	v_pk_fma_f32 v[2:3], v[2:3], 0.5, v[104:105] op_sel_hi:[1,0,1]
	v_pk_fma_f32 v[0:1], v[0:1], 0.5, v[154:155] op_sel_hi:[1,0,1]
	global_store_dwordx4 v[64:65], v[60:63], off nt
	global_store_dwordx4 v[64:65], v[56:59], off offset:64 nt
	global_store_dwordx4 v[48:49], v[44:47], off nt
	global_store_dwordx4 v[48:49], v[40:43], off offset:64 nt
	global_store_dwordx4 v[32:33], v[28:31], off nt
	global_store_dwordx4 v[32:33], v[24:27], off offset:64 nt
	global_store_dwordx4 v[16:17], v[12:15], off nt
	global_store_dwordx4 v[16:17], v[8:11], off offset:64 nt
	global_store_dwordx4 v[16:17], v[4:7], off offset:512 nt
	global_store_dwordx4 v[16:17], v[0:3], off offset:576 nt
	s_cbranch_vccnz .LBB0_914
	s_and_b64 vcc, exec, s[6:7]
	s_cbranch_vccnz .LBB0_913
	s_barrier
	s_branch .LBB0_913
